# baseline (speedup 1.0000x reference)
; __device__ __forceinline__ u16 f2bf(float a) { return (u16)(pack2(a, 0.f) & 0xffffu); }
;   if (dld == 0) dld = K;
;   u16* tl = (u16*)shm;
;   const int t = tid_;
;   {
;     int k = t >> 3, n0 = (t & 7) * 8;
;     const float4* s = (const float4*)(src + (size_t)(kt * 64 + k) * N + ntile * 64 + n0);
;     float4 a = s[0], b = s[1];
;     tl[(n0 + 0) * 66 + k] = f2bf(a.x); tl[(n0 + 1) * 66 + k] = f2bf(a.y);
;     tl[(n0 + 2) * 66 + k] = f2bf(a.z); tl[(n0 + 3) * 66 + k] = f2bf(a.w);
;     tl[(n0 + 4) * 66 + k] = f2bf(b.x); tl[(n0 + 5) * 66 + k] = f2bf(b.y);
;     tl[(n0 + 6) * 66 + k] = f2bf(b.z); tl[(n0 + 7) * 66 + k] = f2bf(b.w);
;   }
;   __syncthreads();
;   {
;     int n = t >> 3, kk0 = (t & 7) * 8;
;     int ng = ntile * 64 + n, np = ng;
;     if (mode == 1) {
;       if (ng >= 1792) { int j = ng - 1792; int hb = 0; if (j >= 1024) { j -= 1024; hb = 32; } np = 1792 + (j >> 5) * 64 + hb + (j & 31); }
;     } else if (mode == 2) {
;       int j = ng, hb = 0; if (j >= DFF) { j -= DFF; hb = 32; } np = (j >> 5) * 64 + hb + (j & 31);
;     }
;     const uint32_t* r = (const uint32_t*)(tl + n * 66 + kk0);
;     uint4 v = make_uint4(r[0], r[1], r[2], r[3]);
;     *(uint4*)(dst + (size_t)np * dld + kt * 64 + kk0) = v;
;   }
;   __syncthreads();
; }
; __global__ void __launch_bounds__(NTHREADS, 2) fwd_megakernel(Params p_arg) {
;     ...
;     for (int t = blockIdx.x; t < NLAYER * 3584; t += gridDim.x) {
;       int l = t / 3584, r = t - l * 3584;
;       u16* wl = WB + (size_t)l * WLAYER_E;
;       if (r < 960) { transpose_tile(pk->w_in + (size_t)l * 1024 * INW, wl + WOFF_IN, 1024, INW, r / 60, r % 60, 1, shm, tid); }
;       else if (r < 1088) { r -= 960; transpose_tile(pk->w_a + (size_t)l * 512 * 1024, wl + WOFF_A, 512, 1024, r / 16, r % 16, 0, shm, tid, 1024); }
;       else if (r < 1216) { r -= 1088; transpose_tile(pk->w_b + (size_t)l * 512 * 1024, wl + WOFF_A + 512, 512, 1024, r / 16, r % 16, 0, shm, tid, 1024); }
;       else if (r < 1472) { r -= 1216; transpose_tile(pk->w_o + (size_t)l * 1024 * 1024, wl + WOFF_O, 1024, 1024, r / 16, r % 16, 0, shm, tid); }
;       else if (r < 2880) { r -= 1472; transpose_tile(pk->w_ffn_in + (size_t)l * 1024 * 2 * DFF, wl + WOFF_FI, 1024, 2 * DFF, r / 88, r % 88, 2, shm, tid); }
;       else { r -= 2880; transpose_tile(pk->w_ffn_out + (size_t)l * DFF * 1024, wl + WOFF_FO, DFF, 1024, r / 16, r % 16, 0, shm, tid); }
.LBB0_37:
	v_xor_b32_e32 v8, 0x4000, v8
	v_xor_b32_e32 v9, 0x4000, v9
	s_add_i32 s31, s31, s3
	s_add_i32 s18, s18, s19
	s_add_i32 s20, s20, s21
	s_cmpk_gt_i32 s31, 0x37ff
	s_cbranch_scc1 .LBB0_59
.LBB0_38:
	s_mul_hi_i32 s4, s31, 0x92492493
	s_add_i32 s4, s4, s31
	s_lshr_b32 s10, s4, 31
	s_ashr_i32 s4, s4, 11
	s_add_i32 s12, s4, s10
	s_mul_i32 s4, s12, 0xfffff200
	s_add_i32 s33, s31, s4
	s_ashr_i32 s13, s12, 31
	s_mul_i32 s10, s12, 0x1c40000
	s_mul_hi_i32 s4, s12, 0x1c40000
	s_waitcnt lgkmcnt(0)
	s_add_u32 s10, s0, s10
	s_addc_u32 s11, s1, s4
	s_cmpk_gt_i32 s33, 0x3bf
	s_mov_b64 s[14:15], -1
	s_cbranch_scc0 .LBB0_56
	s_cmpk_gt_u32 s33, 0x43f
	s_cbranch_scc0 .LBB0_53
	s_cmpk_gt_u32 s33, 0x4bf
	s_cbranch_scc0 .LBB0_50
	s_cmpk_gt_u32 s33, 0x5bf
	s_cbranch_scc0 .LBB0_47
	s_cmpk_gt_u32 s33, 0xb3f
	s_cbranch_scc0 .LBB0_44
	s_load_dwordx2 s[14:15], s[8:9], 0x88
	s_mul_i32 s34, s12, 0xb00000
	s_mul_hi_i32 s4, s12, 0xb00000
	s_mul_i32 s35, s12, 0xffffc800
	v_mov_b32_e32 v5, v3
	s_waitcnt lgkmcnt(0)
	s_add_u32 s14, s14, s34
	s_addc_u32 s15, s15, s4
	s_add_i32 s4, s18, s35
	s_andn2_b32 s4, s4, 63
	s_add_i32 s34, s4, 0xffffd300
	v_add_u32_e32 v6, s34, v1
	v_ashrrev_i32_e32 v7, 31, v6
	v_lshlrev_b64 v[6:7], 12, v[6:7]
	v_lshl_add_u64 v[6:7], s[14:15], 0, v[6:7]
	s_and_b32 s14, s20, 0x3c0
	s_lshl_b32 s4, s14, 2
	v_lshl_add_u64 v[6:7], v[6:7], 0, s[4:5]
	v_lshl_add_u64 v[6:7], v[6:7], 0, v[2:3]
	global_load_dwordx4 v[14:17], v[6:7], off
	global_load_dwordx4 v[18:21], v[6:7], off offset:16
	v_mov_b64_e32 v[6:7], s[10:11]
	v_add_u32_e32 v13, s14, v1
	s_mov_b32 s35, s5
	v_mad_i64_i32 v[6:7], s[14:15], v13, s26, v[6:7]
	v_lshl_add_u64 v[6:7], s[34:35], 1, v[6:7]
	v_lshl_add_u64 v[6:7], v[6:7], 0, v[4:5]
	v_add_co_u32_e32 v6, vcc, 0x1680000, v6
	s_mov_b64 s[14:15], 0
	s_nop 0
	v_addc_co_u32_e32 v7, vcc, 0, v7, vcc
	s_waitcnt vmcnt(1)
	v_cvt_pk_bf16_f32 v5, v14, s0
	v_cvt_pk_bf16_f32 v13, v15, s0
	v_cvt_pk_bf16_f32 v14, v16, s0
	v_cvt_pk_bf16_f32 v15, v17, s0
	s_waitcnt vmcnt(0)
	v_cvt_pk_bf16_f32 v16, v18, s0
	v_cvt_pk_bf16_f32 v17, v19, s0
	v_cvt_pk_bf16_f32 v18, v20, s0
	v_cvt_pk_bf16_f32 v19, v21, s0
	ds_write_b16 v8, v5
	ds_write_b16 v8, v13 offset:132
	ds_write_b16 v8, v14 offset:264
	ds_write_b16 v8, v15 offset:396
	ds_write_b16 v8, v16 offset:528
	ds_write_b16 v8, v17 offset:660
	ds_write_b16 v8, v18 offset:792
	ds_write_b16 v8, v19 offset:924
	s_waitcnt lgkmcnt(0)
	s_barrier
	ds_read2_b32 v[14:15], v9 offset1:1
	ds_read2_b32 v[16:17], v9 offset0:2 offset1:3
	s_waitcnt lgkmcnt(0)
	global_store_dwordx4 v[6:7], v[14:17], off
.LBB0_44:
	s_andn2_b64 vcc, exec, s[14:15]
	s_cbranch_vccnz .LBB0_46
	s_load_dwordx2 s[14:15], s[8:9], 0x80
	s_mul_i32 s34, s12, 0x1600000
	s_mul_hi_i32 s4, s12, 0x1600000
	s_waitcnt lgkmcnt(0)
	s_add_u32 s14, s14, s34
	s_addc_u32 s15, s15, s4
	s_add_i32 s4, s33, 0xfa40
	s_and_b32 s34, s4, 0xffff
	s_mul_i32 s34, s34, 0xba2f
	s_lshr_b32 s35, s34, 16
	s_lshr_b32 s34, s34, 22
	s_mulk_i32 s34, 0x58
	s_sub_i32 s4, s4, s34
	s_and_b32 s34, s35, 0xffc0
	v_add_u32_e32 v5, s34, v1
	v_mov_b64_e32 v[6:7], s[14:15]
	v_mad_i64_i32 v[6:7], s[14:15], v5, s27, v[6:7]
	s_lshl_b32 s4, s4, 6
	s_and_b32 s14, s4, 0xffc0
	s_lshl_b32 s4, s14, 2
	v_lshl_add_u64 v[6:7], v[6:7], 0, s[4:5]
	v_lshl_add_u64 v[6:7], v[6:7], 0, v[2:3]
	global_load_dwordx4 v[14:17], v[6:7], off
	global_load_dwordx4 v[18:21], v[6:7], off offset:16
	v_add_u32_e32 v6, s14, v1
	v_add_u32_e32 v7, 0xfffff500, v6
	v_cmp_lt_i32_e32 vcc, s28, v6
	s_lshl_b32 s4, s34, 1
	v_mov_b32_e32 v5, v3
	v_cndmask_b32_e32 v6, v6, v7, vcc
	v_lshlrev_b32_e32 v7, 1, v6
	v_cndmask_b32_e64 v13, 0, 32, vcc
	v_and_b32_e32 v6, 31, v6
	v_and_b32_e32 v7, 0xffffffc0, v7
	v_or3_b32 v6, v6, v13, v7
	v_ashrrev_i32_e32 v7, 31, v6
	v_lshlrev_b64 v[6:7], 11, v[6:7]
	v_lshl_add_u64 v[6:7], s[10:11], 0, v[6:7]
	v_lshl_add_u64 v[6:7], v[6:7], 0, s[4:5]
	v_lshl_add_u64 v[6:7], v[6:7], 0, v[4:5]
	v_add_co_u32_e32 v6, vcc, 0xb80000, v6
	s_waitcnt vmcnt(1)
	v_cvt_pk_bf16_f32 v5, v14, s0
	v_cvt_pk_bf16_f32 v13, v15, s0
	v_cvt_pk_bf16_f32 v14, v16, s0
	v_cvt_pk_bf16_f32 v15, v17, s0
	s_waitcnt vmcnt(0)
	v_cvt_pk_bf16_f32 v16, v18, s0
	v_cvt_pk_bf16_f32 v17, v19, s0
	v_cvt_pk_bf16_f32 v18, v20, s0
	v_cvt_pk_bf16_f32 v19, v21, s0
	ds_write_b16 v8, v5
	ds_write_b16 v8, v13 offset:132
	ds_write_b16 v8, v14 offset:264
	ds_write_b16 v8, v15 offset:396
	ds_write_b16 v8, v16 offset:528
	ds_write_b16 v8, v17 offset:660
	ds_write_b16 v8, v18 offset:792
	ds_write_b16 v8, v19 offset:924
	s_waitcnt lgkmcnt(0)
	s_barrier
	ds_read2_b32 v[14:15], v9 offset1:1
	ds_read2_b32 v[16:17], v9 offset0:2 offset1:3
	v_addc_co_u32_e32 v7, vcc, 0, v7, vcc
	s_waitcnt lgkmcnt(0)
	global_store_dwordx4 v[6:7], v[14:17], off
.LBB0_46:
	s_mov_b64 s[14:15], 0
; __device__ __forceinline__ u16 f2bf(float a) { return (u16)(pack2(a, 0.f) & 0xffffu); }
;   if (dld == 0) dld = K;
;   u16* tl = (u16*)shm;
;   const int t = tid_;
;   {
;     int k = t >> 3, n0 = (t & 7) * 8;
;     const float4* s = (const float4*)(src + (size_t)(kt * 64 + k) * N + ntile * 64 + n0);
;     float4 a = s[0], b = s[1];
;     tl[(n0 + 0) * 66 + k] = f2bf(a.x); tl[(n0 + 1) * 66 + k] = f2bf(a.y);
;     tl[(n0 + 2) * 66 + k] = f2bf(a.z); tl[(n0 + 3) * 66 + k] = f2bf(a.w);
;     tl[(n0 + 4) * 66 + k] = f2bf(b.x); tl[(n0 + 5) * 66 + k] = f2bf(b.y);
;     tl[(n0 + 6) * 66 + k] = f2bf(b.z); tl[(n0 + 7) * 66 + k] = f2bf(b.w);
;   }
;   __syncthreads();
;   {
;     int n = t >> 3, kk0 = (t & 7) * 8;
;     int ng = ntile * 64 + n, np = ng;
;     if (mode == 1) {
;       if (ng >= 1792) { int j = ng - 1792; int hb = 0; if (j >= 1024) { j -= 1024; hb = 32; } np = 1792 + (j >> 5) * 64 + hb + (j & 31); }
;     } else if (mode == 2) {
;       int j = ng, hb = 0; if (j >= DFF) { j -= DFF; hb = 32; } np = (j >> 5) * 64 + hb + (j & 31);
;     }
;     const uint32_t* r = (const uint32_t*)(tl + n * 66 + kk0);
;     uint4 v = make_uint4(r[0], r[1], r[2], r[3]);
;     *(uint4*)(dst + (size_t)np * dld + kt * 64 + kk0) = v;
;   }
;   __syncthreads();
; }
; __global__ void __launch_bounds__(NTHREADS, 2) fwd_megakernel(Params p_arg) {
;     ...
;       else if (r < 1088) { r -= 960; transpose_tile(pk->w_a + (size_t)l * 512 * 1024, wl + WOFF_A, 512, 1024, r / 16, r % 16, 0, shm, tid, 1024); }
;       else if (r < 1216) { r -= 1088; transpose_tile(pk->w_b + (size_t)l * 512 * 1024, wl + WOFF_A + 512, 512, 1024, r / 16, r % 16, 0, shm, tid, 1024); }
;       else if (r < 1472) { r -= 1216; transpose_tile(pk->w_o + (size_t)l * 1024 * 1024, wl + WOFF_O, 1024, 1024, r / 16, r % 16, 0, shm, tid); }
.LBB0_47:
	s_andn2_b64 vcc, exec, s[14:15]
	s_cbranch_vccnz .LBB0_49
	s_load_dwordx2 s[14:15], s[8:9], 0x70
	s_lshl_b64 s[34:35], s[12:13], 22
	s_mul_i32 s4, s12, 0xffffc800
	v_mov_b32_e32 v5, v3
	s_waitcnt lgkmcnt(0)
	s_add_u32 s14, s14, s34
	s_addc_u32 s15, s15, s35
	s_add_i32 s4, s18, s4
	s_and_b32 s4, s4, 0x1fc0
	s_add_i32 s34, s4, 0xffffed00
	v_add_u32_e32 v6, s34, v1
	v_ashrrev_i32_e32 v7, 31, v6
	s_and_b32 s36, s20, 0x3c0
	v_lshlrev_b64 v[6:7], 12, v[6:7]
	v_lshl_add_u64 v[6:7], s[14:15], 0, v[6:7]
	s_lshl_b32 s4, s36, 2
	v_lshl_add_u64 v[6:7], v[6:7], 0, s[4:5]
	v_lshl_add_u64 v[6:7], v[6:7], 0, v[2:3]
	global_load_dwordx4 v[14:17], v[6:7], off
	global_load_dwordx4 v[18:21], v[6:7], off offset:16
	v_add_u32_e32 v6, s36, v1
	v_ashrrev_i32_e32 v7, 31, v6
	v_lshlrev_b64 v[6:7], 11, v[6:7]
	s_mov_b32 s35, s5
	v_lshl_add_u64 v[6:7], s[10:11], 0, v[6:7]
	v_lshl_add_u64 v[6:7], s[34:35], 1, v[6:7]
	v_lshl_add_u64 v[6:7], v[6:7], 0, v[4:5]
	v_add_co_u32_e32 v6, vcc, 0x980000, v6
	s_waitcnt vmcnt(1)
	v_cvt_pk_bf16_f32 v5, v14, s0
	v_cvt_pk_bf16_f32 v13, v15, s0
	v_cvt_pk_bf16_f32 v14, v16, s0
	v_cvt_pk_bf16_f32 v15, v17, s0
	s_waitcnt vmcnt(0)
	v_cvt_pk_bf16_f32 v16, v18, s0
	v_cvt_pk_bf16_f32 v17, v19, s0
	v_cvt_pk_bf16_f32 v18, v20, s0
	v_cvt_pk_bf16_f32 v19, v21, s0
	ds_write_b16 v8, v5
	ds_write_b16 v8, v13 offset:132
	ds_write_b16 v8, v14 offset:264
	ds_write_b16 v8, v15 offset:396
	ds_write_b16 v8, v16 offset:528
	ds_write_b16 v8, v17 offset:660
	ds_write_b16 v8, v18 offset:792
	ds_write_b16 v8, v19 offset:924
	s_waitcnt lgkmcnt(0)
	s_barrier
	ds_read2_b32 v[14:15], v9 offset1:1
	ds_read2_b32 v[16:17], v9 offset0:2 offset1:3
	v_addc_co_u32_e32 v7, vcc, 0, v7, vcc
	s_waitcnt lgkmcnt(0)
	global_store_dwordx4 v[6:7], v[14:17], off
.LBB0_49:
	s_mov_b64 s[14:15], 0
.LBB0_50:
	s_andn2_b64 vcc, exec, s[14:15]
	s_cbranch_vccnz .LBB0_52
	s_load_dwordx2 s[14:15], s[8:9], 0x68
	s_lshl_b64 s[34:35], s[12:13], 21
	s_mul_i32 s4, s12, 0xffffc800
	v_mov_b32_e32 v5, v3
	s_waitcnt lgkmcnt(0)
	s_add_u32 s14, s14, s34
	s_addc_u32 s15, s15, s35
	s_add_i32 s4, s18, s4
	s_and_b32 s4, s4, 0x1fc0
	s_add_i32 s34, s4, 0xffffef00
	v_add_u32_e32 v6, s34, v1
	v_ashrrev_i32_e32 v7, 31, v6
	s_and_b32 s36, s20, 0x3c0
	v_lshlrev_b64 v[6:7], 12, v[6:7]
	v_lshl_add_u64 v[6:7], s[14:15], 0, v[6:7]
	s_lshl_b32 s4, s36, 2
	v_lshl_add_u64 v[6:7], v[6:7], 0, s[4:5]
	v_lshl_add_u64 v[6:7], v[6:7], 0, v[2:3]
	global_load_dwordx4 v[14:17], v[6:7], off
	global_load_dwordx4 v[18:21], v[6:7], off offset:16
	v_add_u32_e32 v6, s36, v1
	v_ashrrev_i32_e32 v7, 31, v6
	v_lshlrev_b64 v[6:7], 11, v[6:7]
	s_mov_b32 s35, s5
	v_lshl_add_u64 v[6:7], s[10:11], 0, v[6:7]
	v_lshl_add_u64 v[6:7], s[34:35], 1, v[6:7]
	v_lshl_add_u64 v[6:7], v[6:7], 0, v[4:5]
	v_add_co_u32_e32 v6, vcc, 0x780000, v6
	s_waitcnt vmcnt(1)
	v_cvt_pk_bf16_f32 v5, v14, s0
	v_cvt_pk_bf16_f32 v13, v15, s0
	v_cvt_pk_bf16_f32 v14, v16, s0
	v_cvt_pk_bf16_f32 v15, v17, s0
	s_waitcnt vmcnt(0)
	v_cvt_pk_bf16_f32 v16, v18, s0
	v_cvt_pk_bf16_f32 v17, v19, s0
	v_cvt_pk_bf16_f32 v18, v20, s0
	v_cvt_pk_bf16_f32 v19, v21, s0
	ds_write_b16 v8, v5
	ds_write_b16 v8, v13 offset:132
	ds_write_b16 v8, v14 offset:264
	ds_write_b16 v8, v15 offset:396
	ds_write_b16 v8, v16 offset:528
	ds_write_b16 v8, v17 offset:660
	ds_write_b16 v8, v18 offset:792
	ds_write_b16 v8, v19 offset:924
	s_waitcnt lgkmcnt(0)
	s_barrier
	ds_read2_b32 v[14:15], v9 offset1:1
	ds_read2_b32 v[16:17], v9 offset0:2 offset1:3
	v_addc_co_u32_e32 v7, vcc, 0, v7, vcc
	s_waitcnt lgkmcnt(0)
	global_store_dwordx4 v[6:7], v[14:17], off offset:1024
.LBB0_52:
	s_mov_b64 s[14:15], 0
.LBB0_53:
	s_andn2_b64 vcc, exec, s[14:15]
	s_cbranch_vccnz .LBB0_55
	s_load_dwordx2 s[14:15], s[8:9], 0x60
	s_lshl_b64 s[34:35], s[12:13], 21
	s_mul_i32 s4, s12, 0xffffc800
	v_mov_b32_e32 v5, v3
	s_waitcnt lgkmcnt(0)
	s_add_u32 s14, s14, s34
	s_addc_u32 s15, s15, s35
	s_add_i32 s4, s18, s4
	s_and_b32 s4, s4, 0x1fc0
	s_add_i32 s34, s4, 0xfffff100
	v_add_u32_e32 v6, s34, v1
	v_ashrrev_i32_e32 v7, 31, v6
	s_and_b32 s13, s20, 0x3c0
	v_lshlrev_b64 v[6:7], 12, v[6:7]
	v_lshl_add_u64 v[6:7], s[14:15], 0, v[6:7]
	s_lshl_b32 s4, s13, 2
	v_lshl_add_u64 v[6:7], v[6:7], 0, s[4:5]
	v_lshl_add_u64 v[6:7], v[6:7], 0, v[2:3]
	global_load_dwordx4 v[14:17], v[6:7], off
	global_load_dwordx4 v[18:21], v[6:7], off offset:16
	v_add_u32_e32 v6, s13, v1
	v_ashrrev_i32_e32 v7, 31, v6
	v_lshlrev_b64 v[6:7], 11, v[6:7]
	s_mov_b32 s35, s5
	v_lshl_add_u64 v[6:7], s[10:11], 0, v[6:7]
	v_lshl_add_u64 v[6:7], s[34:35], 1, v[6:7]
	v_lshl_add_u64 v[6:7], v[6:7], 0, v[4:5]
	v_add_co_u32_e32 v6, vcc, 0x780000, v6
	s_waitcnt vmcnt(1)
	v_cvt_pk_bf16_f32 v5, v14, s0
	v_cvt_pk_bf16_f32 v13, v15, s0
	v_cvt_pk_bf16_f32 v14, v16, s0
	v_cvt_pk_bf16_f32 v15, v17, s0
	s_waitcnt vmcnt(0)
	v_cvt_pk_bf16_f32 v16, v18, s0
	v_cvt_pk_bf16_f32 v17, v19, s0
	v_cvt_pk_bf16_f32 v18, v20, s0
	v_cvt_pk_bf16_f32 v19, v21, s0
	ds_write_b16 v8, v5
	ds_write_b16 v8, v13 offset:132
	ds_write_b16 v8, v14 offset:264
	ds_write_b16 v8, v15 offset:396
	ds_write_b16 v8, v16 offset:528
	ds_write_b16 v8, v17 offset:660
	ds_write_b16 v8, v18 offset:792
	ds_write_b16 v8, v19 offset:924
	s_waitcnt lgkmcnt(0)
	s_barrier
	ds_read2_b32 v[14:15], v9 offset1:1
	ds_read2_b32 v[16:17], v9 offset0:2 offset1:3
	v_addc_co_u32_e32 v7, vcc, 0, v7, vcc
	s_waitcnt lgkmcnt(0)
	global_store_dwordx4 v[6:7], v[14:17], off
.LBB0_55:
	s_mov_b64 s[14:15], 0

; __device__ __forceinline__ float bf2f(u16 v) { return __uint_as_float(((uint32_t)v) << 16); }
; __device__ __forceinline__ uint2 pack4(float a, float b, float c, float d) { return make_uint2(pack2(a, b), pack2(c, d)); }
; __global__ void __launch_bounds__(NTHREADS, 2) fwd_megakernel(Params p_arg) {
;     ...
;         for (int tt = 0; tt < 8; ++tt) {
;           bf16x8 wf[4];
; #pragma unroll
;           for (int ks = 0; ks < 4; ++ks) wf[ks] = *(const bf16x8*)(wsb + (tt * 16 + fr) * 128 + ks * 32 + fq * 8);
;           f32x4 ac[4];
; #pragma unroll
;           for (int ct = 0; ct < 4; ++ct) ac[ct] = f32x4{0.f, 0.f, 0.f, 0.f};
; #pragma unroll
;           for (int ks = 0; ks < 4; ++ks)
; #pragma unroll
;             for (int ct = 0; ct < 4; ++ct) ac[ct] = __builtin_amdgcn_mfma_f32_16x16x32_bf16(vf[ct][ks], wf[ks], ac[ct], 0, 0, 0);
;           const size_t tok = tok0 + tt * 16 + fr;
;           const float bias = pk->gm_b_s[((size_t)l * 8 + g) * 128 + tt * 16 + fr];
; #pragma unroll
;           for (int cp = 0; cp < 2; ++cp) {
;             uint2 ur[2], ov[2];
;             load_pair16(ZUp + tok * 512 + g * 64 + cp * 32, fq, ur[0], ur[1]);
; #pragma unroll
;             for (int q = 0; q < 2; ++q) {
;               const int ct = cp * 2 + q;
;               float u0 = bf2f((u16)(ur[q].x & 0xffffu)), u1 = bf2f((u16)(ur[q].x >> 16)), u2 = bf2f((u16)(ur[q].y & 0xffffu)), u3 = bf2f((u16)(ur[q].y >> 16));
;               ov[q] = pack4(u0 * (ac[ct][0] + bias), u1 * (ac[ct][1] + bias), u2 * (ac[ct][2] + bias), u3 * (ac[ct][3] + bias));
;             }
;             store_pair16(ABp + tok * 1024 + g * 64 + cp * 32, fq, ov[0], ov[1]);
;           }
;         }
.LBB0_297:
	global_load_dwordx4 v[102:105], v[70:71], off offset:-128
	global_load_dwordx4 v[106:109], v[70:71], off offset:-64
	global_load_dwordx4 v[154:157], v[70:71], off
	global_load_dwordx4 v[158:161], v[70:71], off offset:64
	v_lshl_add_u64 v[72:73], v[88:89], 0, s[10:11]
	global_load_dword v0, v[72:73], off
	v_lshl_add_u64 v[72:73], v[66:67], 0, s[34:35]
	global_load_dwordx4 v[192:195], v[72:73], off
	global_load_dwordx4 v[196:199], v[72:73], off offset:64
	v_lshl_add_u64 v[110:111], v[68:69], 0, s[34:35]
	s_add_u32 s10, s10, 64
	s_addc_u32 s11, s11, 0
	s_mov_b64 s[12:13], 0x8000
	v_lshl_add_u64 v[70:71], v[70:71], 0, s[48:49]
	v_lshl_add_u64 v[66:67], v[66:67], 0, s[94:95]
	v_lshl_add_u64 v[68:69], v[68:69], 0, s[12:13]
	s_cmpk_eq_i32 s10, 0x200
	s_waitcnt vmcnt(6) lgkmcnt(14)
	v_mfma_f32_16x16x32_bf16 v[180:183], v[2:5], v[102:105], 0
	s_waitcnt lgkmcnt(11)
	v_mfma_f32_16x16x32_bf16 v[184:187], v[18:21], v[102:105], 0
	s_waitcnt lgkmcnt(7)
	v_mfma_f32_16x16x32_bf16 v[188:191], v[34:37], v[102:105], 0
	s_waitcnt lgkmcnt(3)
	v_mfma_f32_16x16x32_bf16 v[102:105], v[50:53], v[102:105], 0
	s_waitcnt vmcnt(5)
	v_mfma_f32_16x16x32_bf16 v[180:183], v[6:9], v[106:109], v[180:183]
	v_mfma_f32_16x16x32_bf16 v[184:187], v[22:25], v[106:109], v[184:187]
	v_mfma_f32_16x16x32_bf16 v[188:191], v[38:41], v[106:109], v[188:191]
	s_waitcnt lgkmcnt(2)
	v_mfma_f32_16x16x32_bf16 v[102:105], v[54:57], v[106:109], v[102:105]
	s_waitcnt vmcnt(4)
	v_mfma_f32_16x16x32_bf16 v[106:109], v[10:13], v[154:157], v[180:183]
	v_mfma_f32_16x16x32_bf16 v[180:183], v[26:29], v[154:157], v[184:187]
	v_mfma_f32_16x16x32_bf16 v[184:187], v[42:45], v[154:157], v[188:191]
	s_waitcnt lgkmcnt(1)
	v_mfma_f32_16x16x32_bf16 v[102:105], v[58:61], v[154:157], v[102:105]
	s_waitcnt vmcnt(3)
	v_mfma_f32_16x16x32_bf16 v[106:109], v[14:17], v[158:161], v[106:109]
	v_mfma_f32_16x16x32_bf16 v[154:157], v[30:33], v[158:161], v[180:183]
	v_mfma_f32_16x16x32_bf16 v[180:183], v[46:49], v[158:161], v[184:187]
	s_waitcnt vmcnt(2)
	s_nop 4
	v_pk_add_f32 v[106:107], v[0:1], v[106:107] op_sel_hi:[0,1]
	v_pk_add_f32 v[108:109], v[0:1], v[108:109] op_sel_hi:[0,1]
	v_pk_add_f32 v[154:155], v[0:1], v[154:155] op_sel_hi:[0,1]
	s_waitcnt lgkmcnt(0)
	v_mfma_f32_16x16x32_bf16 v[102:105], v[62:65], v[158:161], v[102:105]
	s_waitcnt vmcnt(1)
	v_mov_b32_e32 v101, v194
	v_mov_b32_e32 v151, v195
	s_nop 0
	v_permlane16_swap_b32_e32 v192, v101
	v_permlane16_swap_b32_e32 v193, v151
	v_lshlrev_b32_e32 v160, 16, v192
	v_and_b32_e32 v161, 0xffff0000, v192
	v_lshlrev_b32_e32 v158, 16, v193
	v_and_b32_e32 v159, 0xffff0000, v193
	v_pk_mul_f32 v[106:107], v[106:107], v[160:161]
	v_pk_mul_f32 v[108:109], v[108:109], v[158:159]
	v_cvt_pk_bf16_f32 v106, v106, v107
	v_cvt_pk_bf16_f32 v107, v108, v109
	v_lshlrev_b32_e32 v108, 16, v101
	v_and_b32_e32 v109, 0xffff0000, v101
	v_lshlrev_b32_e32 v158, 16, v151
	v_and_b32_e32 v159, 0xffff0000, v151
	v_pk_mul_f32 v[108:109], v[154:155], v[108:109]
	v_pk_add_f32 v[154:155], v[0:1], v[156:157] op_sel_hi:[0,1]
	v_pk_mul_f32 v[154:155], v[154:155], v[158:159]
	v_cvt_pk_bf16_f32 v108, v108, v109
	v_cvt_pk_bf16_f32 v109, v154, v155
	s_nop 0
	v_permlane16_swap_b32_e32 v106, v108
	v_permlane16_swap_b32_e32 v107, v109
	global_store_dwordx4 v[110:111], v[106:109], off offset:-64
	v_pk_add_f32 v[102:103], v[0:1], v[102:103] op_sel_hi:[0,1]
	s_waitcnt vmcnt(1)
	v_mov_b32_e32 v101, v198
	s_nop 1
	v_permlane16_swap_b32_e32 v196, v101
	v_mov_b32_e32 v151, v199
	s_nop 1
	v_permlane16_swap_b32_e32 v197, v151
	v_lshlrev_b32_e32 v72, 16, v196
	v_and_b32_e32 v73, 0xffff0000, v196
	v_pk_add_f32 v[108:109], v[0:1], v[180:181] op_sel_hi:[0,1]
	v_lshlrev_b32_e32 v106, 16, v197
	v_and_b32_e32 v107, 0xffff0000, v197
	v_pk_mul_f32 v[72:73], v[108:109], v[72:73]
	v_pk_add_f32 v[108:109], v[0:1], v[182:183] op_sel_hi:[0,1]
	v_pk_mul_f32 v[108:109], v[108:109], v[106:107]
	v_cvt_pk_bf16_f32 v106, v72, v73
	v_lshlrev_b32_e32 v72, 16, v101
	v_and_b32_e32 v73, 0xffff0000, v101
	v_cvt_pk_bf16_f32 v107, v108, v109
	v_lshlrev_b32_e32 v108, 16, v151
	v_and_b32_e32 v109, 0xffff0000, v151
	v_pk_mul_f32 v[72:73], v[102:103], v[72:73]
	v_pk_add_f32 v[102:103], v[0:1], v[104:105] op_sel_hi:[0,1]
	v_pk_mul_f32 v[102:103], v[102:103], v[108:109]
	v_cvt_pk_bf16_f32 v108, v72, v73
	v_cvt_pk_bf16_f32 v109, v102, v103
	s_nop 0
	v_permlane16_swap_b32_e32 v106, v108
	v_permlane16_swap_b32_e32 v107, v109
	global_store_dwordx4 v[110:111], v[106:109], off
	s_cbranch_scc0 .LBB0_297
; __global__ void __launch_bounds__(NTHREADS, 2) fwd_megakernel(Params p_arg) {
;     ...
;         const int qt = wid;
;         const int kt0 = qt < 6 ? qt : 6;
;         const int qi = qt * 16 + fr;
;         const float klo = (nb == 0) ? 128.f : 0.f, khi = (nb == 31) ? 256.f : 384.f;
; #pragma unroll 1
;         for (int g = 0; g < 4; ++g) {
;           const int h = kvh * 4 + g;
;           const size_t tokq = tok0 + qt * 16 + fr;
;           bf16x8 qf[2];
;           qf[0] = *(const bf16x8*)(ZQp + tokq * 512 + h * 64 + fq * 8);
;           qf[1] = *(const bf16x8*)(ZQp + tokq * 512 + h * 64 + 32 + fq * 8);
;           f32x4 S[18];
; #pragma unroll
;           for (int i = 0; i < 18; ++i) {
;             S[i] = f32x4{0.f, 0.f, 0.f, 0.f};
; #pragma unroll
;             for (int ks = 0; ks < 2; ++ks) {
;               bf16x8 kf = *(const bf16x8*)(Ks + ((kt0 + i) * 16 + fr) * 72 + ks * 32 + fq * 8);
;               S[i] = __builtin_amdgcn_mfma_f32_16x16x32_bf16(kf, qf[ks], S[i], 0, 0, 0);
;             }
;             if ((i % 3) == 2) __builtin_amdgcn_sched_barrier(0);
;           }
;           const float slope = exp2f(-(float)(h + 1));
;           const float sinkv = pk->attn_sink[(size_t)l * 8 + h];
;           float d0 = (float)(kt0 * 16 + fq * 4 - 128 - qi);
;           asm volatile("" : "+v"(d0));
;           const float lo2 = fmaxf(-128.f, klo - 128.f - (float)qi), hi2 = fminf(128.f, khi - 129.f - (float)qi);
;           float mx = sinkv;
; #pragma unroll
;           for (int i = 0; i < 18; ++i)
; #pragma unroll
;             for (int r = 0; r < 4; ++r) {
;               float t = d0 + (float)(i * 16 + r);
;               bool ok = (t >= lo2) && (t <= hi2);
;               float v = ok ? (S[i][r] - slope * fabsf(t)) : -1e30f;
;               S[i][r] = v; mx = fmaxf(mx, v);
;             }
	s_and_b32 s1, s99, 31
	s_lshl_b32 s47, s1, 7
	s_cmp_eq_u32 s1, 0
	s_cselect_b64 s[10:11], -1, 0
	s_cmp_eq_u32 s1, 31
	v_cndmask_b32_e64 v0, v165, 0, s[10:11]
	v_sub_f32_e32 v0, v0, v113
	s_cselect_b64 vcc, -1, 0
	v_max_f32_e32 v153, 0xc3000000, v0
	v_cndmask_b32_e32 v0, v254, v168, vcc
	s_addk_i32 s47, 0xff80
	v_sub_f32_e32 v0, v0, v113
	s_add_u32 s0, s0, s36
	v_min_f32_e32 v154, 0x43000000, v0
	v_add_u32_e32 v0, s47, v127
	s_addc_u32 s1, 0, s37
	v_or_b32_e32 v2, s36, v0
	v_mov_b32_e32 v3, s37
	v_lshl_add_u64 v[4:5], s[0:1], 0, v[78:79]
	v_lshlrev_b64 v[2:3], 7, v[2:3]
	v_lshlrev_b64 v[6:7], 10, v[4:5]
	v_lshlrev_b64 v[4:5], 11, v[4:5]
	s_mov_b32 s28, 0
	v_cmp_gt_u32_e64 s[10:11], s38, v0
	v_lshl_add_u64 v[102:103], v[96:97], 0, v[6:7]
	v_lshl_add_u64 v[104:105], v[98:99], 0, v[4:5]
	s_mov_b64 s[12:13], -1
	v_lshlrev_b64 v[106:107], 1, v[2:3]
	v_mov_b32_e32 v249, 0x7f7f0000
	v_add_f32_e32 v247, 0x00000000, v112
	v_cmp_ge_f32_e32 vcc, v247, v153
	v_cmp_le_f32_e64 s[14:15], v247, v154
	v_and_b32_e32 v247, 0x7fffffff, v247
	s_and_b64 vcc, vcc, s[14:15]
	s_nop 1
	v_cndmask_b32_e32 v245, v249, v247, vcc
	v_add_f32_e32 v248, 0x3f800000, v112
	v_cmp_ge_f32_e32 vcc, v248, v153
	v_cmp_le_f32_e64 s[14:15], v248, v154
	v_and_b32_e32 v248, 0x7fffffff, v248
	s_and_b64 vcc, vcc, s[14:15]
	s_nop 1
	v_cndmask_b32_e32 v246, v249, v248, vcc
	v_cvt_pk_bf16_f32 v208, v245, v246
	v_add_f32_e32 v247, 0x40000000, v112
	v_cmp_ge_f32_e32 vcc, v247, v153
	v_cmp_le_f32_e64 s[14:15], v247, v154
	v_and_b32_e32 v247, 0x7fffffff, v247
	s_and_b64 vcc, vcc, s[14:15]
	s_nop 1
	v_cndmask_b32_e32 v245, v249, v247, vcc
	v_add_f32_e32 v248, 0x40400000, v112
	v_cmp_ge_f32_e32 vcc, v248, v153
	v_cmp_le_f32_e64 s[14:15], v248, v154
	v_and_b32_e32 v248, 0x7fffffff, v248
	s_and_b64 vcc, vcc, s[14:15]
	s_nop 1
	v_cndmask_b32_e32 v246, v249, v248, vcc
	v_cvt_pk_bf16_f32 v209, v245, v246
	v_add_f32_e32 v247, 0x41800000, v112
	v_cmp_ge_f32_e32 vcc, v247, v153
	v_cmp_le_f32_e64 s[14:15], v247, v154
	v_and_b32_e32 v247, 0x7fffffff, v247
	s_and_b64 vcc, vcc, s[14:15]
	s_nop 1
	v_cndmask_b32_e32 v245, v249, v247, vcc
	v_add_f32_e32 v248, 0x41880000, v112
	v_cmp_ge_f32_e32 vcc, v248, v153
	v_cmp_le_f32_e64 s[14:15], v248, v154
	v_and_b32_e32 v248, 0x7fffffff, v248
	s_and_b64 vcc, vcc, s[14:15]
	s_nop 1
	v_cndmask_b32_e32 v246, v249, v248, vcc
	v_cvt_pk_bf16_f32 v210, v245, v246
	v_add_f32_e32 v247, 0x41900000, v112
	v_cmp_ge_f32_e32 vcc, v247, v153
	v_cmp_le_f32_e64 s[14:15], v247, v154
	v_and_b32_e32 v247, 0x7fffffff, v247
	s_and_b64 vcc, vcc, s[14:15]
	s_nop 1
	v_cndmask_b32_e32 v245, v249, v247, vcc
	v_add_f32_e32 v248, 0x41980000, v112
	v_cmp_ge_f32_e32 vcc, v248, v153
	v_cmp_le_f32_e64 s[14:15], v248, v154
	v_and_b32_e32 v248, 0x7fffffff, v248
	s_and_b64 vcc, vcc, s[14:15]
	s_nop 1
	v_cndmask_b32_e32 v246, v249, v248, vcc
	v_cvt_pk_bf16_f32 v211, v245, v246
	v_add_f32_e32 v247, 0x42000000, v112
	v_cmp_ge_f32_e32 vcc, v247, v153
	v_cmp_le_f32_e64 s[14:15], v247, v154
	v_and_b32_e32 v247, 0x7fffffff, v247
	s_and_b64 vcc, vcc, s[14:15]
	s_nop 1
	v_cndmask_b32_e32 v245, v249, v247, vcc
	v_add_f32_e32 v248, 0x42040000, v112
	v_cmp_ge_f32_e32 vcc, v248, v153
	v_cmp_le_f32_e64 s[14:15], v248, v154
	v_and_b32_e32 v248, 0x7fffffff, v248
	s_and_b64 vcc, vcc, s[14:15]
	s_nop 1
	v_cndmask_b32_e32 v246, v249, v248, vcc
	v_cvt_pk_bf16_f32 v212, v245, v246
	v_add_f32_e32 v247, 0x42080000, v112
	v_cmp_ge_f32_e32 vcc, v247, v153
	v_cmp_le_f32_e64 s[14:15], v247, v154
	v_and_b32_e32 v247, 0x7fffffff, v247
	s_and_b64 vcc, vcc, s[14:15]
	s_nop 1
	v_cndmask_b32_e32 v245, v249, v247, vcc
	v_add_f32_e32 v248, 0x420c0000, v112
	v_cmp_ge_f32_e32 vcc, v248, v153
	v_cmp_le_f32_e64 s[14:15], v248, v154
	v_and_b32_e32 v248, 0x7fffffff, v248
	s_and_b64 vcc, vcc, s[14:15]
	s_nop 1
	v_cndmask_b32_e32 v246, v249, v248, vcc
	v_cvt_pk_bf16_f32 v213, v245, v246
	v_add_f32_e32 v247, 0x42400000, v112
	v_cmp_ge_f32_e32 vcc, v247, v153
	v_cmp_le_f32_e64 s[14:15], v247, v154
	v_and_b32_e32 v247, 0x7fffffff, v247
	s_and_b64 vcc, vcc, s[14:15]
	s_nop 1
	v_cndmask_b32_e32 v245, v249, v247, vcc
	v_add_f32_e32 v248, 0x42440000, v112
	v_cmp_ge_f32_e32 vcc, v248, v153
	v_cmp_le_f32_e64 s[14:15], v248, v154
	v_and_b32_e32 v248, 0x7fffffff, v248
	s_and_b64 vcc, vcc, s[14:15]
	s_nop 1
	v_cndmask_b32_e32 v246, v249, v248, vcc
	v_cvt_pk_bf16_f32 v214, v245, v246
	v_add_f32_e32 v247, 0x42480000, v112
	v_cmp_ge_f32_e32 vcc, v247, v153
	v_cmp_le_f32_e64 s[14:15], v247, v154
	v_and_b32_e32 v247, 0x7fffffff, v247
	s_and_b64 vcc, vcc, s[14:15]
	s_nop 1
	v_cndmask_b32_e32 v245, v249, v247, vcc
	v_add_f32_e32 v248, 0x424c0000, v112
	v_cmp_ge_f32_e32 vcc, v248, v153
	v_cmp_le_f32_e64 s[14:15], v248, v154
	v_and_b32_e32 v248, 0x7fffffff, v248
	s_and_b64 vcc, vcc, s[14:15]
	s_nop 1
	v_cndmask_b32_e32 v246, v249, v248, vcc
	v_cvt_pk_bf16_f32 v215, v245, v246
	v_add_f32_e32 v247, 0x42800000, v112
	v_cmp_ge_f32_e32 vcc, v247, v153
	v_cmp_le_f32_e64 s[14:15], v247, v154
	v_and_b32_e32 v247, 0x7fffffff, v247
	s_and_b64 vcc, vcc, s[14:15]
	s_nop 1
	v_cndmask_b32_e32 v245, v249, v247, vcc
	v_add_f32_e32 v248, 0x42820000, v112
	v_cmp_ge_f32_e32 vcc, v248, v153
	v_cmp_le_f32_e64 s[14:15], v248, v154
	v_and_b32_e32 v248, 0x7fffffff, v248
	s_and_b64 vcc, vcc, s[14:15]
	s_nop 1
	v_cndmask_b32_e32 v246, v249, v248, vcc
	v_cvt_pk_bf16_f32 v216, v245, v246
	v_add_f32_e32 v247, 0x42840000, v112
	v_cmp_ge_f32_e32 vcc, v247, v153
	v_cmp_le_f32_e64 s[14:15], v247, v154
	v_and_b32_e32 v247, 0x7fffffff, v247
	s_and_b64 vcc, vcc, s[14:15]
	s_nop 1
	v_cndmask_b32_e32 v245, v249, v247, vcc
	v_add_f32_e32 v248, 0x42860000, v112
	v_cmp_ge_f32_e32 vcc, v248, v153
; __global__ void __launch_bounds__(NTHREADS, 2) fwd_megakernel(Params p_arg) {
;     ...
;           float d0 = (float)(kt0 * 16 + fq * 4 - 128 - qi);
;           asm volatile("" : "+v"(d0));
;           const float lo2 = fmaxf(-128.f, klo - 128.f - (float)qi), hi2 = fminf(128.f, khi - 129.f - (float)qi);
;           float mx = sinkv;
; #pragma unroll
;           for (int i = 0; i < 18; ++i)
; #pragma unroll
;             for (int r = 0; r < 4; ++r) {
;               float t = d0 + (float)(i * 16 + r);
;               bool ok = (t >= lo2) && (t <= hi2);
;               float v = ok ? (S[i][r] - slope * fabsf(t)) : -1e30f;
;               S[i][r] = v; mx = fmaxf(mx, v);
	v_cmp_le_f32_e64 s[14:15], v248, v154
	v_and_b32_e32 v248, 0x7fffffff, v248
	s_and_b64 vcc, vcc, s[14:15]
	s_nop 1
	v_cndmask_b32_e32 v246, v249, v248, vcc
	v_cvt_pk_bf16_f32 v217, v245, v246
	v_add_f32_e32 v247, 0x42a00000, v112
	v_cmp_ge_f32_e32 vcc, v247, v153
	v_cmp_le_f32_e64 s[14:15], v247, v154
	v_and_b32_e32 v247, 0x7fffffff, v247
	s_and_b64 vcc, vcc, s[14:15]
	s_nop 1
	v_cndmask_b32_e32 v245, v249, v247, vcc
	v_add_f32_e32 v248, 0x42a20000, v112
	v_cmp_ge_f32_e32 vcc, v248, v153
	v_cmp_le_f32_e64 s[14:15], v248, v154
	v_and_b32_e32 v248, 0x7fffffff, v248
	s_and_b64 vcc, vcc, s[14:15]
	s_nop 1
	v_cndmask_b32_e32 v246, v249, v248, vcc
	v_cvt_pk_bf16_f32 v218, v245, v246
	v_add_f32_e32 v247, 0x42a40000, v112
	v_cmp_ge_f32_e32 vcc, v247, v153
	v_cmp_le_f32_e64 s[14:15], v247, v154
	v_and_b32_e32 v247, 0x7fffffff, v247
	s_and_b64 vcc, vcc, s[14:15]
	s_nop 1
	v_cndmask_b32_e32 v245, v249, v247, vcc
	v_add_f32_e32 v248, 0x42a60000, v112
	v_cmp_ge_f32_e32 vcc, v248, v153
	v_cmp_le_f32_e64 s[14:15], v248, v154
	v_and_b32_e32 v248, 0x7fffffff, v248
	s_and_b64 vcc, vcc, s[14:15]
	s_nop 1
	v_cndmask_b32_e32 v246, v249, v248, vcc
	v_cvt_pk_bf16_f32 v219, v245, v246
	v_add_f32_e32 v247, 0x42c00000, v112
	v_cmp_ge_f32_e32 vcc, v247, v153
	v_cmp_le_f32_e64 s[14:15], v247, v154
	v_and_b32_e32 v247, 0x7fffffff, v247
	s_and_b64 vcc, vcc, s[14:15]
	s_nop 1
	v_cndmask_b32_e32 v245, v249, v247, vcc
	v_add_f32_e32 v248, 0x42c20000, v112
	v_cmp_ge_f32_e32 vcc, v248, v153
	v_cmp_le_f32_e64 s[14:15], v248, v154
	v_and_b32_e32 v248, 0x7fffffff, v248
	s_and_b64 vcc, vcc, s[14:15]
	s_nop 1
	v_cndmask_b32_e32 v246, v249, v248, vcc
	v_cvt_pk_bf16_f32 v220, v245, v246
	v_add_f32_e32 v247, 0x42c40000, v112
	v_cmp_ge_f32_e32 vcc, v247, v153
	v_cmp_le_f32_e64 s[14:15], v247, v154
	v_and_b32_e32 v247, 0x7fffffff, v247
	s_and_b64 vcc, vcc, s[14:15]
	s_nop 1
	v_cndmask_b32_e32 v245, v249, v247, vcc
	v_add_f32_e32 v248, 0x42c60000, v112
	v_cmp_ge_f32_e32 vcc, v248, v153
	v_cmp_le_f32_e64 s[14:15], v248, v154
	v_and_b32_e32 v248, 0x7fffffff, v248
	s_and_b64 vcc, vcc, s[14:15]
	s_nop 1
	v_cndmask_b32_e32 v246, v249, v248, vcc
	v_cvt_pk_bf16_f32 v221, v245, v246
	v_add_f32_e32 v247, 0x42e00000, v112
	v_cmp_ge_f32_e32 vcc, v247, v153
	v_cmp_le_f32_e64 s[14:15], v247, v154
	v_and_b32_e32 v247, 0x7fffffff, v247
	s_and_b64 vcc, vcc, s[14:15]
	s_nop 1
	v_cndmask_b32_e32 v245, v249, v247, vcc
	v_add_f32_e32 v248, 0x42e20000, v112
	v_cmp_ge_f32_e32 vcc, v248, v153
	v_cmp_le_f32_e64 s[14:15], v248, v154
	v_and_b32_e32 v248, 0x7fffffff, v248
	s_and_b64 vcc, vcc, s[14:15]
	s_nop 1
	v_cndmask_b32_e32 v246, v249, v248, vcc
	v_cvt_pk_bf16_f32 v222, v245, v246
	v_add_f32_e32 v247, 0x42e40000, v112
	v_cmp_ge_f32_e32 vcc, v247, v153
	v_cmp_le_f32_e64 s[14:15], v247, v154
	v_and_b32_e32 v247, 0x7fffffff, v247
	s_and_b64 vcc, vcc, s[14:15]
	s_nop 1
	v_cndmask_b32_e32 v245, v249, v247, vcc
	v_add_f32_e32 v248, 0x42e60000, v112
	v_cmp_ge_f32_e32 vcc, v248, v153
	v_cmp_le_f32_e64 s[14:15], v248, v154
	v_and_b32_e32 v248, 0x7fffffff, v248
	s_and_b64 vcc, vcc, s[14:15]
	s_nop 1
	v_cndmask_b32_e32 v246, v249, v248, vcc
	v_cvt_pk_bf16_f32 v223, v245, v246
	v_add_f32_e32 v247, 0x43000000, v112
	v_cmp_ge_f32_e32 vcc, v247, v153
	v_cmp_le_f32_e64 s[14:15], v247, v154
	v_and_b32_e32 v247, 0x7fffffff, v247
	s_and_b64 vcc, vcc, s[14:15]
	s_nop 1
	v_cndmask_b32_e32 v245, v249, v247, vcc
	v_add_f32_e32 v248, 0x43010000, v112
	v_cmp_ge_f32_e32 vcc, v248, v153
	v_cmp_le_f32_e64 s[14:15], v248, v154
	v_and_b32_e32 v248, 0x7fffffff, v248
	s_and_b64 vcc, vcc, s[14:15]
	s_nop 1
	v_cndmask_b32_e32 v246, v249, v248, vcc
	v_cvt_pk_bf16_f32 v224, v245, v246
	v_add_f32_e32 v247, 0x43020000, v112
	v_cmp_ge_f32_e32 vcc, v247, v153
	v_cmp_le_f32_e64 s[14:15], v247, v154
	v_and_b32_e32 v247, 0x7fffffff, v247
	s_and_b64 vcc, vcc, s[14:15]
	s_nop 1
	v_cndmask_b32_e32 v245, v249, v247, vcc
	v_add_f32_e32 v248, 0x43030000, v112
	v_cmp_ge_f32_e32 vcc, v248, v153
	v_cmp_le_f32_e64 s[14:15], v248, v154
	v_and_b32_e32 v248, 0x7fffffff, v248
	s_and_b64 vcc, vcc, s[14:15]
	s_nop 1
	v_cndmask_b32_e32 v246, v249, v248, vcc
	v_cvt_pk_bf16_f32 v225, v245, v246
	v_add_f32_e32 v247, 0x43100000, v112
	v_cmp_ge_f32_e32 vcc, v247, v153
	v_cmp_le_f32_e64 s[14:15], v247, v154
	v_and_b32_e32 v247, 0x7fffffff, v247
	s_and_b64 vcc, vcc, s[14:15]
	s_nop 1
	v_cndmask_b32_e32 v245, v249, v247, vcc
	v_add_f32_e32 v248, 0x43110000, v112
	v_cmp_ge_f32_e32 vcc, v248, v153
	v_cmp_le_f32_e64 s[14:15], v248, v154
	v_and_b32_e32 v248, 0x7fffffff, v248
	s_and_b64 vcc, vcc, s[14:15]
	s_nop 1
	v_cndmask_b32_e32 v246, v249, v248, vcc
	v_cvt_pk_bf16_f32 v226, v245, v246
	v_add_f32_e32 v247, 0x43120000, v112
	v_cmp_ge_f32_e32 vcc, v247, v153
	v_cmp_le_f32_e64 s[14:15], v247, v154
	v_and_b32_e32 v247, 0x7fffffff, v247
	s_and_b64 vcc, vcc, s[14:15]
	s_nop 1
	v_cndmask_b32_e32 v245, v249, v247, vcc
	v_add_f32_e32 v248, 0x43130000, v112
	v_cmp_ge_f32_e32 vcc, v248, v153
	v_cmp_le_f32_e64 s[14:15], v248, v154
	v_and_b32_e32 v248, 0x7fffffff, v248
	s_and_b64 vcc, vcc, s[14:15]
	s_nop 1
	v_cndmask_b32_e32 v246, v249, v248, vcc
	v_cvt_pk_bf16_f32 v227, v245, v246
	v_add_f32_e32 v247, 0x43200000, v112
	v_cmp_ge_f32_e32 vcc, v247, v153
	v_cmp_le_f32_e64 s[14:15], v247, v154
	v_and_b32_e32 v247, 0x7fffffff, v247
	s_and_b64 vcc, vcc, s[14:15]
	s_nop 1
	v_cndmask_b32_e32 v245, v249, v247, vcc
	v_add_f32_e32 v248, 0x43210000, v112
	v_cmp_ge_f32_e32 vcc, v248, v153
	v_cmp_le_f32_e64 s[14:15], v248, v154
	v_and_b32_e32 v248, 0x7fffffff, v248
	s_and_b64 vcc, vcc, s[14:15]
	s_nop 1
	v_cndmask_b32_e32 v246, v249, v248, vcc
	v_cvt_pk_bf16_f32 v228, v245, v246
; __global__ void __launch_bounds__(NTHREADS, 2) fwd_megakernel(Params p_arg) {
;     ...
;           float d0 = (float)(kt0 * 16 + fq * 4 - 128 - qi);
;           asm volatile("" : "+v"(d0));
;           const float lo2 = fmaxf(-128.f, klo - 128.f - (float)qi), hi2 = fminf(128.f, khi - 129.f - (float)qi);
;           float mx = sinkv;
; #pragma unroll
;           for (int i = 0; i < 18; ++i)
; #pragma unroll
;             for (int r = 0; r < 4; ++r) {
;               float t = d0 + (float)(i * 16 + r);
;               bool ok = (t >= lo2) && (t <= hi2);
;               float v = ok ? (S[i][r] - slope * fabsf(t)) : -1e30f;
;               S[i][r] = v; mx = fmaxf(mx, v);
	v_add_f32_e32 v247, 0x43220000, v112
	v_cmp_ge_f32_e32 vcc, v247, v153
	v_cmp_le_f32_e64 s[14:15], v247, v154
	v_and_b32_e32 v247, 0x7fffffff, v247
	s_and_b64 vcc, vcc, s[14:15]
	s_nop 1
	v_cndmask_b32_e32 v245, v249, v247, vcc
	v_add_f32_e32 v248, 0x43230000, v112
	v_cmp_ge_f32_e32 vcc, v248, v153
	v_cmp_le_f32_e64 s[14:15], v248, v154
	v_and_b32_e32 v248, 0x7fffffff, v248
	s_and_b64 vcc, vcc, s[14:15]
	s_nop 1
	v_cndmask_b32_e32 v246, v249, v248, vcc
	v_cvt_pk_bf16_f32 v229, v245, v246
	v_add_f32_e32 v247, 0x43300000, v112
	v_cmp_ge_f32_e32 vcc, v247, v153
	v_cmp_le_f32_e64 s[14:15], v247, v154
	v_and_b32_e32 v247, 0x7fffffff, v247
	s_and_b64 vcc, vcc, s[14:15]
	s_nop 1
	v_cndmask_b32_e32 v245, v249, v247, vcc
	v_add_f32_e32 v248, 0x43310000, v112
	v_cmp_ge_f32_e32 vcc, v248, v153
	v_cmp_le_f32_e64 s[14:15], v248, v154
	v_and_b32_e32 v248, 0x7fffffff, v248
	s_and_b64 vcc, vcc, s[14:15]
	s_nop 1
	v_cndmask_b32_e32 v246, v249, v248, vcc
	v_cvt_pk_bf16_f32 v230, v245, v246
	v_add_f32_e32 v247, 0x43320000, v112
	v_cmp_ge_f32_e32 vcc, v247, v153
	v_cmp_le_f32_e64 s[14:15], v247, v154
	v_and_b32_e32 v247, 0x7fffffff, v247
	s_and_b64 vcc, vcc, s[14:15]
	s_nop 1
	v_cndmask_b32_e32 v245, v249, v247, vcc
	v_add_f32_e32 v248, 0x43330000, v112
	v_cmp_ge_f32_e32 vcc, v248, v153
	v_cmp_le_f32_e64 s[14:15], v248, v154
	v_and_b32_e32 v248, 0x7fffffff, v248
	s_and_b64 vcc, vcc, s[14:15]
	s_nop 1
	v_cndmask_b32_e32 v246, v249, v248, vcc
	v_cvt_pk_bf16_f32 v231, v245, v246
	v_add_f32_e32 v247, 0x43400000, v112
	v_cmp_ge_f32_e32 vcc, v247, v153
	v_cmp_le_f32_e64 s[14:15], v247, v154
	v_and_b32_e32 v247, 0x7fffffff, v247
	s_and_b64 vcc, vcc, s[14:15]
	s_nop 1
	v_cndmask_b32_e32 v245, v249, v247, vcc
	v_add_f32_e32 v248, 0x43410000, v112
	v_cmp_ge_f32_e32 vcc, v248, v153
	v_cmp_le_f32_e64 s[14:15], v248, v154
	v_and_b32_e32 v248, 0x7fffffff, v248
	s_and_b64 vcc, vcc, s[14:15]
	s_nop 1
	v_cndmask_b32_e32 v246, v249, v248, vcc
	v_cvt_pk_bf16_f32 v232, v245, v246
	v_add_f32_e32 v247, 0x43420000, v112
	v_cmp_ge_f32_e32 vcc, v247, v153
	v_cmp_le_f32_e64 s[14:15], v247, v154
	v_and_b32_e32 v247, 0x7fffffff, v247
	s_and_b64 vcc, vcc, s[14:15]
	s_nop 1
	v_cndmask_b32_e32 v245, v249, v247, vcc
	v_add_f32_e32 v248, 0x43430000, v112
	v_cmp_ge_f32_e32 vcc, v248, v153
	v_cmp_le_f32_e64 s[14:15], v248, v154
	v_and_b32_e32 v248, 0x7fffffff, v248
	s_and_b64 vcc, vcc, s[14:15]
	s_nop 1
	v_cndmask_b32_e32 v246, v249, v248, vcc
	v_cvt_pk_bf16_f32 v233, v245, v246
	v_add_f32_e32 v247, 0x43500000, v112
	v_cmp_ge_f32_e32 vcc, v247, v153
	v_cmp_le_f32_e64 s[14:15], v247, v154
	v_and_b32_e32 v247, 0x7fffffff, v247
	s_and_b64 vcc, vcc, s[14:15]
	s_nop 1
	v_cndmask_b32_e32 v245, v249, v247, vcc
	v_add_f32_e32 v248, 0x43510000, v112
	v_cmp_ge_f32_e32 vcc, v248, v153
	v_cmp_le_f32_e64 s[14:15], v248, v154
	v_and_b32_e32 v248, 0x7fffffff, v248
	s_and_b64 vcc, vcc, s[14:15]
	s_nop 1
	v_cndmask_b32_e32 v246, v249, v248, vcc
	v_cvt_pk_bf16_f32 v234, v245, v246
	v_add_f32_e32 v247, 0x43520000, v112
	v_cmp_ge_f32_e32 vcc, v247, v153
	v_cmp_le_f32_e64 s[14:15], v247, v154
	v_and_b32_e32 v247, 0x7fffffff, v247
	s_and_b64 vcc, vcc, s[14:15]
	s_nop 1
	v_cndmask_b32_e32 v245, v249, v247, vcc
	v_add_f32_e32 v248, 0x43530000, v112
	v_cmp_ge_f32_e32 vcc, v248, v153
	v_cmp_le_f32_e64 s[14:15], v248, v154
	v_and_b32_e32 v248, 0x7fffffff, v248
	s_and_b64 vcc, vcc, s[14:15]
	s_nop 1
	v_cndmask_b32_e32 v246, v249, v248, vcc
	v_cvt_pk_bf16_f32 v235, v245, v246
	v_add_f32_e32 v247, 0x43600000, v112
	v_cmp_ge_f32_e32 vcc, v247, v153
	v_cmp_le_f32_e64 s[14:15], v247, v154
	v_and_b32_e32 v247, 0x7fffffff, v247
	s_and_b64 vcc, vcc, s[14:15]
	s_nop 1
	v_cndmask_b32_e32 v245, v249, v247, vcc
	v_add_f32_e32 v248, 0x43610000, v112
; __global__ void __launch_bounds__(NTHREADS, 2) fwd_megakernel(Params p_arg) {
;     ...
;           float d0 = (float)(kt0 * 16 + fq * 4 - 128 - qi);
;           asm volatile("" : "+v"(d0));
;           const float lo2 = fmaxf(-128.f, klo - 128.f - (float)qi), hi2 = fminf(128.f, khi - 129.f - (float)qi);
;           float mx = sinkv;
; #pragma unroll
;           for (int i = 0; i < 18; ++i)
; #pragma unroll
;             for (int r = 0; r < 4; ++r) {
;               float t = d0 + (float)(i * 16 + r);
;               bool ok = (t >= lo2) && (t <= hi2);
;               float v = ok ? (S[i][r] - slope * fabsf(t)) : -1e30f;
;               S[i][r] = v; mx = fmaxf(mx, v);
	v_cmp_ge_f32_e32 vcc, v248, v153
	v_cmp_le_f32_e64 s[14:15], v248, v154
	v_and_b32_e32 v248, 0x7fffffff, v248
	s_and_b64 vcc, vcc, s[14:15]
	s_nop 1
	v_cndmask_b32_e32 v246, v249, v248, vcc
	v_cvt_pk_bf16_f32 v236, v245, v246
	v_add_f32_e32 v247, 0x43620000, v112
	v_cmp_ge_f32_e32 vcc, v247, v153
	v_cmp_le_f32_e64 s[14:15], v247, v154
	v_and_b32_e32 v247, 0x7fffffff, v247
	s_and_b64 vcc, vcc, s[14:15]
	s_nop 1
	v_cndmask_b32_e32 v245, v249, v247, vcc
	v_add_f32_e32 v248, 0x43630000, v112
	v_cmp_ge_f32_e32 vcc, v248, v153
	v_cmp_le_f32_e64 s[14:15], v248, v154
	v_and_b32_e32 v248, 0x7fffffff, v248
	s_and_b64 vcc, vcc, s[14:15]
	s_nop 1
	v_cndmask_b32_e32 v246, v249, v248, vcc
	v_cvt_pk_bf16_f32 v237, v245, v246
	v_add_f32_e32 v247, 0x43700000, v112
	v_cmp_ge_f32_e32 vcc, v247, v153
	v_cmp_le_f32_e64 s[14:15], v247, v154
	v_and_b32_e32 v247, 0x7fffffff, v247
	s_and_b64 vcc, vcc, s[14:15]
	s_nop 1
	v_cndmask_b32_e32 v245, v249, v247, vcc
	v_add_f32_e32 v248, 0x43710000, v112
	v_cmp_ge_f32_e32 vcc, v248, v153
	v_cmp_le_f32_e64 s[14:15], v248, v154
	v_and_b32_e32 v248, 0x7fffffff, v248
	s_and_b64 vcc, vcc, s[14:15]
	s_nop 1
	v_cndmask_b32_e32 v246, v249, v248, vcc
	v_cvt_pk_bf16_f32 v238, v245, v246
	v_add_f32_e32 v247, 0x43720000, v112
	v_cmp_ge_f32_e32 vcc, v247, v153
	v_cmp_le_f32_e64 s[14:15], v247, v154
	v_and_b32_e32 v247, 0x7fffffff, v247
	s_and_b64 vcc, vcc, s[14:15]
	s_nop 1
	v_cndmask_b32_e32 v245, v249, v247, vcc
	v_add_f32_e32 v248, 0x43730000, v112
	v_cmp_ge_f32_e32 vcc, v248, v153
	v_cmp_le_f32_e64 s[14:15], v248, v154
	v_and_b32_e32 v248, 0x7fffffff, v248
	s_and_b64 vcc, vcc, s[14:15]
	s_nop 1
	v_cndmask_b32_e32 v246, v249, v248, vcc
	v_cvt_pk_bf16_f32 v239, v245, v246
	v_add_f32_e32 v247, 0x43800000, v112
	v_cmp_ge_f32_e32 vcc, v247, v153
	v_cmp_le_f32_e64 s[14:15], v247, v154
	v_and_b32_e32 v247, 0x7fffffff, v247
	s_and_b64 vcc, vcc, s[14:15]
	s_nop 1
	v_cndmask_b32_e32 v245, v249, v247, vcc
	v_add_f32_e32 v248, 0x43808000, v112
	v_cmp_ge_f32_e32 vcc, v248, v153
	v_cmp_le_f32_e64 s[14:15], v248, v154
	v_and_b32_e32 v248, 0x7fffffff, v248
	s_and_b64 vcc, vcc, s[14:15]
	s_nop 1
	v_cndmask_b32_e32 v246, v249, v248, vcc
	v_cvt_pk_bf16_f32 v240, v245, v246
	v_add_f32_e32 v247, 0x43810000, v112
	v_cmp_ge_f32_e32 vcc, v247, v153
	v_cmp_le_f32_e64 s[14:15], v247, v154
	v_and_b32_e32 v247, 0x7fffffff, v247
	s_and_b64 vcc, vcc, s[14:15]
	s_nop 1
	v_cndmask_b32_e32 v245, v249, v247, vcc
	v_add_f32_e32 v248, 0x43818000, v112
	v_cmp_ge_f32_e32 vcc, v248, v153
	v_cmp_le_f32_e64 s[14:15], v248, v154
	v_and_b32_e32 v248, 0x7fffffff, v248
	s_and_b64 vcc, vcc, s[14:15]
	s_nop 1
	v_cndmask_b32_e32 v246, v249, v248, vcc
	v_cvt_pk_bf16_f32 v241, v245, v246
	v_add_f32_e32 v247, 0x43880000, v112
	v_cmp_ge_f32_e32 vcc, v247, v153
	v_cmp_le_f32_e64 s[14:15], v247, v154
	v_and_b32_e32 v247, 0x7fffffff, v247
	s_and_b64 vcc, vcc, s[14:15]
	s_nop 1
	v_cndmask_b32_e32 v245, v249, v247, vcc
	v_add_f32_e32 v248, 0x43888000, v112
	v_cmp_ge_f32_e32 vcc, v248, v153
	v_cmp_le_f32_e64 s[14:15], v248, v154
	v_and_b32_e32 v248, 0x7fffffff, v248
	s_and_b64 vcc, vcc, s[14:15]
	s_nop 1
	v_cndmask_b32_e32 v246, v249, v248, vcc
	v_cvt_pk_bf16_f32 v242, v245, v246
	v_add_f32_e32 v247, 0x43890000, v112
	v_cmp_ge_f32_e32 vcc, v247, v153
	v_cmp_le_f32_e64 s[14:15], v247, v154
	v_and_b32_e32 v247, 0x7fffffff, v247
	s_and_b64 vcc, vcc, s[14:15]
	s_nop 1
	v_cndmask_b32_e32 v245, v249, v247, vcc
	v_add_f32_e32 v248, 0x43898000, v112
	v_cmp_ge_f32_e32 vcc, v248, v153
	v_cmp_le_f32_e64 s[14:15], v248, v154
	v_and_b32_e32 v248, 0x7fffffff, v248
	s_and_b64 vcc, vcc, s[14:15]
	s_nop 1
	v_cndmask_b32_e32 v246, v249, v248, vcc
	v_cvt_pk_bf16_f32 v243, v245, v246
	s_barrier

; __global__ void __launch_bounds__(NTHREADS, 2) fwd_megakernel(Params p_arg) {
;     ...
;           const size_t tokq = tok0 + qt * 16 + fr;
;           bf16x8 qf[2];
;           qf[0] = *(const bf16x8*)(ZQp + tokq * 512 + h * 64 + fq * 8);
;           qf[1] = *(const bf16x8*)(ZQp + tokq * 512 + h * 64 + 32 + fq * 8);
;           f32x4 S[18];
; #pragma unroll
;           for (int i = 0; i < 18; ++i) {
;             S[i] = f32x4{0.f, 0.f, 0.f, 0.f};
; #pragma unroll
;             for (int ks = 0; ks < 2; ++ks) {
;               bf16x8 kf = *(const bf16x8*)(Ks + ((kt0 + i) * 16 + fr) * 72 + ks * 32 + fq * 8);
;               S[i] = __builtin_amdgcn_mfma_f32_16x16x32_bf16(kf, qf[ks], S[i], 0, 0, 0);
;             }
;             if ((i % 3) == 2) __builtin_amdgcn_sched_barrier(0);
;           }
.Lq_go:
	v_mov_b32_e32 v2, v200
	v_mov_b32_e32 v3, v201
	v_mov_b32_e32 v4, v202
	v_mov_b32_e32 v5, v203
	v_mov_b32_e32 v156, v204
	v_mov_b32_e32 v157, v205
	v_mov_b32_e32 v158, v206
	v_mov_b32_e32 v159, v207
	v_lshl_add_u64 v[6:7], v[108:109], 0, s[24:25]
	global_load_dwordx4 v[200:203], v[6:7], off offset:64
	global_load_dwordx4 v[204:207], v[6:7], off offset:128
	ds_read_b128 v[6:9], v133
	ds_read_b128 v[10:13], v133 offset:64
	s_waitcnt lgkmcnt(1)
	v_mfma_f32_16x16x32_bf16 v[6:9], v[6:9], v[2:5], 0
	s_waitcnt lgkmcnt(0)
	v_mfma_f32_16x16x32_bf16 v[70:73], v[10:13], v[156:159], v[6:9]
	ds_read_b128 v[10:13], v134 offset:64
	s_nop 4
	ds_read_b128 v[6:9], v134
	s_waitcnt lgkmcnt(0)
	v_mfma_f32_16x16x32_bf16 v[6:9], v[6:9], v[2:5], 0
	v_mfma_f32_16x16x32_bf16 v[66:69], v[10:13], v[156:159], v[6:9]
	ds_read_b128 v[10:13], v135 offset:64
	s_nop 5
	ds_read_b128 v[6:9], v135
	s_waitcnt lgkmcnt(0)
	v_mfma_f32_16x16x32_bf16 v[6:9], v[6:9], v[2:5], 0
	v_mfma_f32_16x16x32_bf16 v[62:65], v[10:13], v[156:159], v[6:9]
	s_nop 6
	ds_read_b128 v[6:9], v136
	ds_read_b128 v[10:13], v136 offset:64
	ds_read_b128 v[14:17], v137
	ds_read_b128 v[18:21], v137 offset:64
	s_waitcnt lgkmcnt(3)
	v_mfma_f32_16x16x32_bf16 v[6:9], v[6:9], v[2:5], 0
	s_waitcnt lgkmcnt(2)
	v_mfma_f32_16x16x32_bf16 v[58:61], v[10:13], v[156:159], v[6:9]
	ds_read_b128 v[10:13], v138 offset:64
	s_nop 4
	ds_read_b128 v[6:9], v138
	s_waitcnt lgkmcnt(3)
	v_mfma_f32_16x16x32_bf16 v[14:17], v[14:17], v[2:5], 0
	s_waitcnt lgkmcnt(0)
	v_mfma_f32_16x16x32_bf16 v[6:9], v[6:9], v[2:5], 0
	v_mfma_f32_16x16x32_bf16 v[54:57], v[18:21], v[156:159], v[14:17]
	v_mfma_f32_16x16x32_bf16 v[50:53], v[10:13], v[156:159], v[6:9]
	s_nop 5
	ds_read_b128 v[6:9], v139
	ds_read_b128 v[10:13], v139 offset:64
	ds_read_b128 v[14:17], v140
	ds_read_b128 v[18:21], v140 offset:64
	s_waitcnt lgkmcnt(3)
	v_mfma_f32_16x16x32_bf16 v[6:9], v[6:9], v[2:5], 0
	s_waitcnt lgkmcnt(2)
	v_mfma_f32_16x16x32_bf16 v[46:49], v[10:13], v[156:159], v[6:9]
	ds_read_b128 v[10:13], v141 offset:64
	s_nop 4
	ds_read_b128 v[6:9], v141
	s_waitcnt lgkmcnt(3)
	v_mfma_f32_16x16x32_bf16 v[14:17], v[14:17], v[2:5], 0
	s_waitcnt lgkmcnt(0)
	v_mfma_f32_16x16x32_bf16 v[6:9], v[6:9], v[2:5], 0
	v_mfma_f32_16x16x32_bf16 v[42:45], v[18:21], v[156:159], v[14:17]
	v_mfma_f32_16x16x32_bf16 v[38:41], v[10:13], v[156:159], v[6:9]
	s_nop 5
	ds_read_b128 v[6:9], v142
	ds_read_b128 v[10:13], v142 offset:64
	ds_read_b128 v[14:17], v143
	ds_read_b128 v[18:21], v143 offset:64
	s_waitcnt lgkmcnt(3)
	v_mfma_f32_16x16x32_bf16 v[6:9], v[6:9], v[2:5], 0
	s_waitcnt lgkmcnt(2)
	v_mfma_f32_16x16x32_bf16 v[34:37], v[10:13], v[156:159], v[6:9]
	ds_read_b128 v[10:13], v144 offset:64
	s_nop 4
	ds_read_b128 v[6:9], v144
	s_waitcnt lgkmcnt(3)
	v_mfma_f32_16x16x32_bf16 v[14:17], v[14:17], v[2:5], 0
	s_waitcnt lgkmcnt(0)
	v_mfma_f32_16x16x32_bf16 v[6:9], v[6:9], v[2:5], 0
	v_mfma_f32_16x16x32_bf16 v[30:33], v[18:21], v[156:159], v[14:17]
	v_mfma_f32_16x16x32_bf16 v[26:29], v[10:13], v[156:159], v[6:9]
	s_nop 5
	ds_read_b128 v[6:9], v145
	ds_read_b128 v[10:13], v145 offset:64
	ds_read_b128 v[14:17], v146
	ds_read_b128 v[18:21], v146 offset:64
	s_waitcnt lgkmcnt(3)
	v_mfma_f32_16x16x32_bf16 v[6:9], v[6:9], v[2:5], 0
	s_waitcnt lgkmcnt(2)
	v_mfma_f32_16x16x32_bf16 v[22:25], v[10:13], v[156:159], v[6:9]
	ds_read_b128 v[10:13], v147 offset:64
	s_nop 4
	ds_read_b128 v[6:9], v147
	s_waitcnt lgkmcnt(3)
	v_mfma_f32_16x16x32_bf16 v[14:17], v[14:17], v[2:5], 0
	s_waitcnt lgkmcnt(0)
	v_mfma_f32_16x16x32_bf16 v[6:9], v[6:9], v[2:5], 0
	v_mfma_f32_16x16x32_bf16 v[18:21], v[18:21], v[156:159], v[14:17]
	v_mfma_f32_16x16x32_bf16 v[14:17], v[10:13], v[156:159], v[6:9]
	s_nop 5
	ds_read_b128 v[6:9], v148
	ds_read_b128 v[10:13], v148 offset:64
	s_waitcnt lgkmcnt(1)
	v_mfma_f32_16x16x32_bf16 v[6:9], v[6:9], v[2:5], 0
	ds_read_b128 v[180:183], v150 offset:64
	s_waitcnt lgkmcnt(1)
	v_mfma_f32_16x16x32_bf16 v[10:13], v[10:13], v[156:159], v[6:9]
	s_nop 4
	ds_read_b128 v[6:9], v150
	s_waitcnt lgkmcnt(0)
	v_mfma_f32_16x16x32_bf16 v[6:9], v[6:9], v[2:5], 0
	v_mfma_f32_16x16x32_bf16 v[6:9], v[180:183], v[156:159], v[6:9]
	ds_read_b128 v[180:183], v152
	s_waitcnt lgkmcnt(0)
	v_mfma_f32_16x16x32_bf16 v[2:5], v[180:183], v[2:5], 0
	ds_read_b128 v[180:183], v152 offset:64
	s_waitcnt lgkmcnt(0)
; __global__ void __launch_bounds__(NTHREADS, 2) fwd_megakernel(Params p_arg) {
;     ...
;           const float slope = exp2f(-(float)(h + 1));
;           const float sinkv = pk->attn_sink[(size_t)l * 8 + h];
;           float d0 = (float)(kt0 * 16 + fq * 4 - 128 - qi);
;           asm volatile("" : "+v"(d0));
;           const float lo2 = fmaxf(-128.f, klo - 128.f - (float)qi), hi2 = fminf(128.f, khi - 129.f - (float)qi);
;           float mx = sinkv;
; #pragma unroll
;           for (int i = 0; i < 18; ++i)
; #pragma unroll
;             for (int r = 0; r < 4; ++r) {
;               float t = d0 + (float)(i * 16 + r);
;               bool ok = (t >= lo2) && (t <= hi2);
;               float v = ok ? (S[i][r] - slope * fabsf(t)) : -1e30f;
;               S[i][r] = v; mx = fmaxf(mx, v);
;             }
	v_mfma_f32_16x16x32_bf16 v[2:5], v[180:183], v[156:159], v[2:5]
	v_cvt_f32_u32_e32 v0, s0
	s_mov_b32 s1, 0x42fc0000
	v_mov_b32_e32 v155, v112
	v_cmp_lt_f32_e32 vcc, s1, v0
	s_and_b64 s[14:15], vcc, exec
	s_nop 0
	v_cndmask_b32_e32 v101, 0, v178, vcc
	v_sub_f32_e32 v0, v101, v0
	v_exp_f32_e32 v0, v0
	s_cselect_b32 s1, 0xffffffc0, 0
	v_ldexp_f32 v101, v0, s1
	global_load_dword v0, v1, s[12:13]
	s_nop 0
	v_lshlrev_b32_e32 v245, 16, v208
	v_fma_f32 v70, -v101, v245, v70
	v_and_b32_e32 v246, 0xffff0000, v208
	v_fma_f32 v71, -v101, v246, v71
	v_lshlrev_b32_e32 v245, 16, v209
	v_fma_f32 v72, -v101, v245, v72
	v_and_b32_e32 v246, 0xffff0000, v209
	v_fma_f32 v73, -v101, v246, v73
	v_lshlrev_b32_e32 v245, 16, v210
	v_fma_f32 v66, -v101, v245, v66
	v_and_b32_e32 v246, 0xffff0000, v210
	v_fma_f32 v67, -v101, v246, v67
	v_lshlrev_b32_e32 v245, 16, v211
	v_fma_f32 v68, -v101, v245, v68
	v_and_b32_e32 v246, 0xffff0000, v211
	v_fma_f32 v69, -v101, v246, v69
	v_lshlrev_b32_e32 v245, 16, v212
	v_fma_f32 v62, -v101, v245, v62
	v_and_b32_e32 v246, 0xffff0000, v212
	v_fma_f32 v63, -v101, v246, v63
	v_lshlrev_b32_e32 v245, 16, v213
	v_fma_f32 v64, -v101, v245, v64
	v_and_b32_e32 v246, 0xffff0000, v213
	v_fma_f32 v65, -v101, v246, v65
	v_lshlrev_b32_e32 v245, 16, v214
	v_fma_f32 v58, -v101, v245, v58
	v_and_b32_e32 v246, 0xffff0000, v214
	v_fma_f32 v59, -v101, v246, v59
	v_lshlrev_b32_e32 v245, 16, v215
	v_fma_f32 v60, -v101, v245, v60
	v_and_b32_e32 v246, 0xffff0000, v215
	v_fma_f32 v61, -v101, v246, v61
	v_lshlrev_b32_e32 v245, 16, v216
	v_fma_f32 v54, -v101, v245, v54
	v_and_b32_e32 v246, 0xffff0000, v216
	v_fma_f32 v55, -v101, v246, v55
	v_lshlrev_b32_e32 v245, 16, v217
	v_fma_f32 v56, -v101, v245, v56
	v_and_b32_e32 v246, 0xffff0000, v217
	v_fma_f32 v57, -v101, v246, v57
	v_lshlrev_b32_e32 v245, 16, v218
	v_fma_f32 v50, -v101, v245, v50
	v_and_b32_e32 v246, 0xffff0000, v218
	v_fma_f32 v51, -v101, v246, v51
	v_lshlrev_b32_e32 v245, 16, v219
	v_fma_f32 v52, -v101, v245, v52
	v_and_b32_e32 v246, 0xffff0000, v219
	v_fma_f32 v53, -v101, v246, v53
	v_lshlrev_b32_e32 v245, 16, v220
	v_fma_f32 v46, -v101, v245, v46
	v_and_b32_e32 v246, 0xffff0000, v220
	v_fma_f32 v47, -v101, v246, v47
	v_lshlrev_b32_e32 v245, 16, v221
	v_fma_f32 v48, -v101, v245, v48
	v_and_b32_e32 v246, 0xffff0000, v221
	v_fma_f32 v49, -v101, v246, v49
	v_lshlrev_b32_e32 v245, 16, v222
	v_fma_f32 v42, -v101, v245, v42
	v_and_b32_e32 v246, 0xffff0000, v222
	v_fma_f32 v43, -v101, v246, v43
	v_lshlrev_b32_e32 v245, 16, v223
	v_fma_f32 v44, -v101, v245, v44
	v_and_b32_e32 v246, 0xffff0000, v223
	v_fma_f32 v45, -v101, v246, v45
	v_lshlrev_b32_e32 v245, 16, v224
	v_fma_f32 v38, -v101, v245, v38
	v_and_b32_e32 v246, 0xffff0000, v224
	v_fma_f32 v156, -v101, v246, v39
	v_lshlrev_b32_e32 v245, 16, v225
	v_fma_f32 v40, -v101, v245, v40
	v_and_b32_e32 v246, 0xffff0000, v225
	v_fma_f32 v157, -v101, v246, v41
	v_lshlrev_b32_e32 v245, 16, v226
	v_fma_f32 v34, -v101, v245, v34
	v_and_b32_e32 v246, 0xffff0000, v226
	v_fma_f32 v158, -v101, v246, v35
	v_lshlrev_b32_e32 v245, 16, v227
	v_fma_f32 v36, -v101, v245, v36
	v_and_b32_e32 v246, 0xffff0000, v227
	v_fma_f32 v159, -v101, v246, v37
	v_lshlrev_b32_e32 v245, 16, v228
	v_fma_f32 v30, -v101, v245, v30
	v_and_b32_e32 v246, 0xffff0000, v228
	v_fma_f32 v160, -v101, v246, v31
	v_lshlrev_b32_e32 v245, 16, v229
	v_fma_f32 v32, -v101, v245, v32
	v_and_b32_e32 v246, 0xffff0000, v229
	v_fma_f32 v161, -v101, v246, v33
	v_lshlrev_b32_e32 v245, 16, v230
	v_fma_f32 v26, -v101, v245, v26
	v_and_b32_e32 v246, 0xffff0000, v230
	v_fma_f32 v180, -v101, v246, v27
	v_lshlrev_b32_e32 v245, 16, v231
	v_fma_f32 v28, -v101, v245, v28
	v_and_b32_e32 v246, 0xffff0000, v231
	v_fma_f32 v181, -v101, v246, v29
	v_lshlrev_b32_e32 v245, 16, v232
	v_fma_f32 v22, -v101, v245, v22
	v_and_b32_e32 v246, 0xffff0000, v232
	v_fma_f32 v182, -v101, v246, v23
	v_lshlrev_b32_e32 v245, 16, v233
	v_fma_f32 v24, -v101, v245, v24
	v_and_b32_e32 v246, 0xffff0000, v233
	v_fma_f32 v183, -v101, v246, v25
	v_lshlrev_b32_e32 v245, 16, v234
	v_fma_f32 v18, -v101, v245, v18
	v_and_b32_e32 v246, 0xffff0000, v234
	v_fma_f32 v184, -v101, v246, v19
	v_lshlrev_b32_e32 v245, 16, v235
	v_fma_f32 v20, -v101, v245, v20
	v_and_b32_e32 v246, 0xffff0000, v235
	v_fma_f32 v186, -v101, v246, v21
	v_lshlrev_b32_e32 v245, 16, v236
	v_fma_f32 v185, -v101, v245, v14
	v_and_b32_e32 v246, 0xffff0000, v236
	v_fma_f32 v15, -v101, v246, v15
	v_lshlrev_b32_e32 v245, 16, v237
	v_fma_f32 v187, -v101, v245, v16
	v_and_b32_e32 v246, 0xffff0000, v237
	v_fma_f32 v189, -v101, v246, v17
	v_lshlrev_b32_e32 v245, 16, v238
	v_fma_f32 v188, -v101, v245, v10
	v_and_b32_e32 v246, 0xffff0000, v238
	v_fma_f32 v190, -v101, v246, v11
	v_lshlrev_b32_e32 v245, 16, v239
	v_fma_f32 v12, -v101, v245, v12
	v_and_b32_e32 v246, 0xffff0000, v239
	v_fma_f32 v192, -v101, v246, v13
	v_lshlrev_b32_e32 v245, 16, v240
	v_fma_f32 v191, -v101, v245, v6
	v_and_b32_e32 v246, 0xffff0000, v240
	v_fma_f32 v7, -v101, v246, v7
	v_lshlrev_b32_e32 v245, 16, v241
	v_fma_f32 v193, -v101, v245, v8
	v_and_b32_e32 v246, 0xffff0000, v241
	v_fma_f32 v195, -v101, v246, v9
	v_lshlrev_b32_e32 v245, 16, v242
	v_fma_f32 v194, -v101, v245, v2
	v_and_b32_e32 v246, 0xffff0000, v242
	v_fma_f32 v196, -v101, v246, v3
	v_lshlrev_b32_e32 v245, 16, v243
	v_fma_f32 v198, -v101, v245, v4
	v_and_b32_e32 v246, 0xffff0000, v243
	v_fma_f32 v199, -v101, v246, v5
	s_waitcnt vmcnt(0)
; __global__ void __launch_bounds__(NTHREADS, 2) fwd_megakernel(Params p_arg) {
;     ...
;           float mx = sinkv;
; #pragma unroll
;           for (int i = 0; i < 18; ++i)
; #pragma unroll
;             for (int r = 0; r < 4; ++r) {
;               float t = d0 + (float)(i * 16 + r);
;               bool ok = (t >= lo2) && (t <= hi2);
;               float v = ok ? (S[i][r] - slope * fabsf(t)) : -1e30f;
;               S[i][r] = v; mx = fmaxf(mx, v);
;             }
;           mx = fmaxf(mx, __shfl_xor(mx, 16)); mx = fmaxf(mx, __shfl_xor(mx, 32));
;           float sum = 0.f;
; #pragma unroll
;           for (int i = 0; i < 18; ++i)
; #pragma unroll
;             for (int r = 0; r < 4; ++r) { float pv = __expf(S[i][r] - mx); S[i][r] = pv; sum += pv; }
	v_max3_f32 v244, v0, v70, v71
	v_max3_f32 v244, v244, v72, v73
	v_max3_f32 v244, v244, v66, v67
	v_max3_f32 v244, v244, v68, v69
	v_max3_f32 v244, v244, v62, v63
	v_max3_f32 v244, v244, v64, v65
	v_max3_f32 v244, v244, v58, v59
	v_max3_f32 v244, v244, v60, v61
	v_max3_f32 v244, v244, v54, v55
	v_max3_f32 v244, v244, v56, v57
	v_max3_f32 v244, v244, v50, v51
	v_max3_f32 v244, v244, v52, v53
	v_max3_f32 v244, v244, v46, v47
	v_max3_f32 v244, v244, v48, v49
	v_max3_f32 v244, v244, v42, v43
	v_max3_f32 v244, v244, v44, v45
	v_max3_f32 v244, v244, v38, v156
	v_max3_f32 v244, v244, v40, v157
	v_max3_f32 v244, v244, v34, v158
	v_max3_f32 v244, v244, v36, v159
	v_max3_f32 v244, v244, v30, v160
	v_max3_f32 v244, v244, v32, v161
	v_max3_f32 v244, v244, v26, v180
	v_max3_f32 v244, v244, v28, v181
	v_max3_f32 v244, v244, v22, v182
	v_max3_f32 v244, v244, v24, v183
	v_max3_f32 v244, v244, v18, v184
	v_max3_f32 v244, v244, v20, v186
	v_max3_f32 v244, v244, v185, v15
	v_max3_f32 v244, v244, v187, v189
	v_max3_f32 v244, v244, v188, v190
	v_max3_f32 v244, v244, v12, v192
	v_max3_f32 v244, v244, v191, v7
	v_max3_f32 v244, v244, v193, v195
	v_cmp_lt_i32_e32 vcc, v169, v164
	v_max3_f32 v244, v244, v194, v196
	v_max3_f32 v2, v244, v198, v199
	v_cndmask_b32_e32 v3, v163, v169, vcc
	v_lshlrev_b32_e32 v101, 2, v3
	ds_bpermute_b32 v3, v101, v2
	v_cmp_lt_i32_e32 vcc, v170, v164
	s_waitcnt lgkmcnt(0)
	v_max_f32_e32 v3, v3, v3
	v_max_f32_e32 v2, v2, v3
	v_cndmask_b32_e32 v3, v163, v170, vcc
	v_lshlrev_b32_e32 v155, 2, v3
	ds_bpermute_b32 v3, v155, v2
	s_waitcnt lgkmcnt(0)
	v_max_f32_e32 v3, v3, v3
	v_max_f32_e32 v197, v2, v3
	v_sub_f32_e32 v3, v71, v197
	v_mul_f32_e32 v3, 0x3fb8aa3b, v3
	v_exp_f32_e32 v71, v3
	v_sub_f32_e32 v3, v72, v197
	v_mul_f32_e32 v3, 0x3fb8aa3b, v3
	v_exp_f32_e32 v72, v3
	v_sub_f32_e32 v3, v73, v197
	v_mul_f32_e32 v3, 0x3fb8aa3b, v3
	v_exp_f32_e32 v73, v3
	v_sub_f32_e32 v3, v66, v197
	v_mul_f32_e32 v3, 0x3fb8aa3b, v3
	v_exp_f32_e32 v66, v3
	v_sub_f32_e32 v3, v67, v197
	v_mul_f32_e32 v3, 0x3fb8aa3b, v3
	v_exp_f32_e32 v67, v3
	v_sub_f32_e32 v3, v68, v197
	v_mul_f32_e32 v3, 0x3fb8aa3b, v3
	v_exp_f32_e32 v68, v3
	v_sub_f32_e32 v3, v69, v197
	v_mul_f32_e32 v3, 0x3fb8aa3b, v3
	v_exp_f32_e32 v69, v3
	v_sub_f32_e32 v3, v62, v197
	v_mul_f32_e32 v3, 0x3fb8aa3b, v3
	v_exp_f32_e32 v62, v3
	v_sub_f32_e32 v3, v63, v197
	v_mul_f32_e32 v3, 0x3fb8aa3b, v3
	v_exp_f32_e32 v63, v3
	v_sub_f32_e32 v3, v64, v197
	v_mul_f32_e32 v3, 0x3fb8aa3b, v3
	v_exp_f32_e32 v64, v3
	v_sub_f32_e32 v3, v65, v197
	v_mul_f32_e32 v3, 0x3fb8aa3b, v3
	v_exp_f32_e32 v65, v3
	v_sub_f32_e32 v3, v58, v197
	v_mul_f32_e32 v3, 0x3fb8aa3b, v3
	v_exp_f32_e32 v58, v3
	v_sub_f32_e32 v3, v59, v197
	v_mul_f32_e32 v3, 0x3fb8aa3b, v3
	v_exp_f32_e32 v59, v3
	v_sub_f32_e32 v3, v60, v197
	v_mul_f32_e32 v3, 0x3fb8aa3b, v3
	v_exp_f32_e32 v60, v3
	v_sub_f32_e32 v3, v61, v197
	v_mul_f32_e32 v3, 0x3fb8aa3b, v3
	v_exp_f32_e32 v61, v3
	v_sub_f32_e32 v3, v54, v197
	v_mul_f32_e32 v3, 0x3fb8aa3b, v3
	v_exp_f32_e32 v35, v3
	v_sub_f32_e32 v3, v55, v197
	v_mul_f32_e32 v3, 0x3fb8aa3b, v3
	v_exp_f32_e32 v39, v3
	v_sub_f32_e32 v3, v56, v197
	v_mul_f32_e32 v3, 0x3fb8aa3b, v3
	v_exp_f32_e32 v54, v3
	v_sub_f32_e32 v3, v57, v197
	v_mul_f32_e32 v3, 0x3fb8aa3b, v3
	v_exp_f32_e32 v55, v3
	v_sub_f32_e32 v3, v50, v197
	v_mul_f32_e32 v3, 0x3fb8aa3b, v3
	v_exp_f32_e32 v50, v3
	v_sub_f32_e32 v3, v51, v197
	v_mul_f32_e32 v3, 0x3fb8aa3b, v3
	v_exp_f32_e32 v56, v3
	v_sub_f32_e32 v3, v52, v197
	v_mul_f32_e32 v3, 0x3fb8aa3b, v3
	v_exp_f32_e32 v57, v3
	v_sub_f32_e32 v3, v53, v197
	v_mul_f32_e32 v3, 0x3fb8aa3b, v3
	v_exp_f32_e32 v53, v3
	v_sub_f32_e32 v3, v46, v197
	v_mul_f32_e32 v3, 0x3fb8aa3b, v3
	v_exp_f32_e32 v27, v3
	v_sub_f32_e32 v3, v47, v197
	v_mul_f32_e32 v3, 0x3fb8aa3b, v3
	v_exp_f32_e32 v31, v3
	v_sub_f32_e32 v3, v48, v197
	v_mul_f32_e32 v3, 0x3fb8aa3b, v3
	v_exp_f32_e32 v37, v3
	v_sub_f32_e32 v3, v49, v197
	v_mul_f32_e32 v3, 0x3fb8aa3b, v3
	v_exp_f32_e32 v41, v3
	v_sub_f32_e32 v3, v42, v197
	v_mul_f32_e32 v3, 0x3fb8aa3b, v3
	v_exp_f32_e32 v46, v3
	v_sub_f32_e32 v3, v43, v197
	v_mul_f32_e32 v3, 0x3fb8aa3b, v3
	v_exp_f32_e32 v48, v3
	v_sub_f32_e32 v3, v44, v197
	v_mul_f32_e32 v3, 0x3fb8aa3b, v3
	v_exp_f32_e32 v51, v3
	v_sub_f32_e32 v3, v45, v197
	v_sub_f32_e32 v2, v70, v197
	v_mul_f32_e32 v3, 0x3fb8aa3b, v3
	v_mul_f32_e32 v2, 0x3fb8aa3b, v2
	v_exp_f32_e32 v52, v3
	v_sub_f32_e32 v3, v38, v197
	v_exp_f32_e32 v70, v2
	v_mul_f32_e32 v3, 0x3fb8aa3b, v3
	v_exp_f32_e32 v19, v3
	v_sub_f32_e32 v3, v156, v197
	v_mul_f32_e32 v3, 0x3fb8aa3b, v3
	v_exp_f32_e32 v23, v3
	v_sub_f32_e32 v3, v40, v197
	v_add_f32_e32 v2, 0, v70
	v_mul_f32_e32 v3, 0x3fb8aa3b, v3
	v_add_f32_e32 v2, v2, v71
	v_exp_f32_e32 v29, v3
	v_sub_f32_e32 v3, v157, v197
	v_add_f32_e32 v2, v2, v72
	v_mul_f32_e32 v3, 0x3fb8aa3b, v3
	v_add_f32_e32 v2, v2, v73
	v_exp_f32_e32 v33, v3
	v_sub_f32_e32 v3, v34, v197
	v_add_f32_e32 v2, v2, v66
	v_mul_f32_e32 v3, 0x3fb8aa3b, v3
	v_add_f32_e32 v2, v2, v67
	v_exp_f32_e32 v42, v3
	v_sub_f32_e32 v3, v158, v197
	v_add_f32_e32 v2, v2, v68
	v_mul_f32_e32 v3, 0x3fb8aa3b, v3
	v_add_f32_e32 v2, v2, v69
	v_exp_f32_e32 v44, v3
	v_sub_f32_e32 v3, v36, v197
	v_add_f32_e32 v2, v2, v62
	v_mul_f32_e32 v3, 0x3fb8aa3b, v3
	v_add_f32_e32 v2, v2, v63
	v_exp_f32_e32 v47, v3
	v_sub_f32_e32 v3, v159, v197
	v_add_f32_e32 v2, v2, v64
	v_mul_f32_e32 v3, 0x3fb8aa3b, v3
	v_add_f32_e32 v2, v2, v65
	v_exp_f32_e32 v49, v3
	v_sub_f32_e32 v3, v30, v197
	v_add_f32_e32 v2, v2, v58
	v_mul_f32_e32 v3, 0x3fb8aa3b, v3
	v_add_f32_e32 v2, v2, v59
	v_exp_f32_e32 v13, v3
	v_sub_f32_e32 v3, v160, v197
	v_add_f32_e32 v2, v2, v60
	v_mul_f32_e32 v3, 0x3fb8aa3b, v3
	v_add_f32_e32 v2, v2, v61
; __device__ __forceinline__ float rcpf(float x) { return __builtin_amdgcn_rcpf(x); }
; __global__ void __launch_bounds__(NTHREADS, 2) fwd_megakernel(Params p_arg) {
;     ...
;           float sum = 0.f;
; #pragma unroll
;           for (int i = 0; i < 18; ++i)
; #pragma unroll
;             for (int r = 0; r < 4; ++r) { float pv = __expf(S[i][r] - mx); S[i][r] = pv; sum += pv; }
;           sum += __shfl_xor(sum, 16); sum += __shfl_xor(sum, 32);
;           const float inv = rcpf(sum + __expf(sinkv - mx));
;           f32x4 O[4];
; #pragma unroll
;           for (int dt = 0; dt < 4; ++dt) O[dt] = f32x4{0.f, 0.f, 0.f, 0.f};
; #pragma unroll
;           for (int pp = 0; pp < 9; ++pp) {
;             union { bf16x8 v; uint32_t u[4]; } pf;
;             pf.u[0] = pack2(S[2*pp][0], S[2*pp][1]); pf.u[1] = pack2(S[2*pp][2], S[2*pp][3]);
;             pf.u[2] = pack2(S[2*pp+1][0], S[2*pp+1][1]); pf.u[3] = pack2(S[2*pp+1][2], S[2*pp+1][3]);
; #pragma unroll
;             for (int dt = 0; dt < 4; ++dt) {
;               union { bf16x8 v; uint2 h2[2]; } vfr;
;               const u16* vb = VT + (dt * 16 + fr) * 392 + (kt0 + 2 * pp) * 16 + fq * 4;
;               vfr.h2[0] = *(const uint2*)(vb);
;               vfr.h2[1] = *(const uint2*)(vb + 16);
;               O[dt] = __builtin_amdgcn_mfma_f32_16x16x32_bf16(vfr.v, pf.v, O[dt], 0, 0, 0);
	v_exp_f32_e32 v16, v3
	v_sub_f32_e32 v3, v32, v197
	v_add_f32_e32 v2, v2, v35
	v_mul_f32_e32 v3, 0x3fb8aa3b, v3
	v_add_f32_e32 v2, v2, v39
	v_exp_f32_e32 v21, v3
	v_sub_f32_e32 v3, v161, v197
	v_add_f32_e32 v2, v2, v54
	v_mul_f32_e32 v3, 0x3fb8aa3b, v3
	v_add_f32_e32 v2, v2, v55
	v_exp_f32_e32 v25, v3
	v_sub_f32_e32 v3, v26, v197
	v_add_f32_e32 v2, v2, v50
	v_mul_f32_e32 v3, 0x3fb8aa3b, v3
	v_add_f32_e32 v2, v2, v56
	v_exp_f32_e32 v34, v3
	v_sub_f32_e32 v3, v180, v197
	v_add_f32_e32 v2, v2, v57
	v_mul_f32_e32 v3, 0x3fb8aa3b, v3
	v_add_f32_e32 v2, v2, v53
	v_exp_f32_e32 v38, v3
	v_sub_f32_e32 v3, v28, v197
	v_add_f32_e32 v2, v2, v27
	v_mul_f32_e32 v3, 0x3fb8aa3b, v3
	v_add_f32_e32 v2, v2, v31
	v_exp_f32_e32 v43, v3
	v_sub_f32_e32 v3, v181, v197
	v_add_f32_e32 v2, v2, v37
	v_mul_f32_e32 v3, 0x3fb8aa3b, v3
	v_add_f32_e32 v2, v2, v41
	v_exp_f32_e32 v45, v3
	v_sub_f32_e32 v3, v22, v197
	v_add_f32_e32 v2, v2, v46
	v_mul_f32_e32 v3, 0x3fb8aa3b, v3
	v_add_f32_e32 v2, v2, v48
	v_exp_f32_e32 v8, v3
	v_sub_f32_e32 v3, v182, v197
	v_add_f32_e32 v2, v2, v51
	v_mul_f32_e32 v3, 0x3fb8aa3b, v3
	v_add_f32_e32 v2, v2, v52
	v_exp_f32_e32 v10, v3
	v_sub_f32_e32 v3, v24, v197
	v_add_f32_e32 v2, v2, v19
	v_mul_f32_e32 v3, 0x3fb8aa3b, v3
	v_add_f32_e32 v2, v2, v23
	v_exp_f32_e32 v14, v3
	v_sub_f32_e32 v3, v183, v197
	v_add_f32_e32 v2, v2, v29
	v_mul_f32_e32 v3, 0x3fb8aa3b, v3
	v_add_f32_e32 v2, v2, v33
	v_exp_f32_e32 v17, v3
	v_sub_f32_e32 v3, v18, v197
	v_add_f32_e32 v2, v2, v42
	v_mul_f32_e32 v3, 0x3fb8aa3b, v3
	v_add_f32_e32 v2, v2, v44
	v_exp_f32_e32 v26, v3
	v_sub_f32_e32 v3, v184, v197
	v_add_f32_e32 v2, v2, v47
	v_mul_f32_e32 v3, 0x3fb8aa3b, v3
	v_add_f32_e32 v2, v2, v49
	v_exp_f32_e32 v30, v3
	v_sub_f32_e32 v3, v20, v197
	v_add_f32_e32 v2, v2, v13
	v_mul_f32_e32 v3, 0x3fb8aa3b, v3
	v_add_f32_e32 v2, v2, v16
	v_exp_f32_e32 v36, v3
	v_sub_f32_e32 v3, v186, v197
	v_add_f32_e32 v2, v2, v21
	v_mul_f32_e32 v3, 0x3fb8aa3b, v3
	v_add_f32_e32 v2, v2, v25
	v_exp_f32_e32 v40, v3
	v_sub_f32_e32 v3, v185, v197
	v_add_f32_e32 v2, v2, v34
	v_mul_f32_e32 v3, 0x3fb8aa3b, v3
	v_add_f32_e32 v2, v2, v38
	v_exp_f32_e32 v4, v3
	v_sub_f32_e32 v3, v15, v197
	v_add_f32_e32 v2, v2, v43
	v_mul_f32_e32 v3, 0x3fb8aa3b, v3
	v_add_f32_e32 v2, v2, v45
	v_exp_f32_e32 v6, v3
	v_sub_f32_e32 v3, v187, v197
	v_add_f32_e32 v2, v2, v8
	v_mul_f32_e32 v3, 0x3fb8aa3b, v3
	v_add_f32_e32 v2, v2, v10
	v_exp_f32_e32 v9, v3
	v_sub_f32_e32 v3, v189, v197
	v_add_f32_e32 v2, v2, v14
	v_mul_f32_e32 v3, 0x3fb8aa3b, v3
	v_add_f32_e32 v2, v2, v17
	v_exp_f32_e32 v11, v3
	v_sub_f32_e32 v3, v188, v197
	v_add_f32_e32 v2, v2, v26
	v_mul_f32_e32 v3, 0x3fb8aa3b, v3
	v_add_f32_e32 v2, v2, v30
	v_exp_f32_e32 v18, v3
	v_sub_f32_e32 v3, v190, v197
	v_add_f32_e32 v2, v2, v36
	v_mul_f32_e32 v3, 0x3fb8aa3b, v3
	v_add_f32_e32 v2, v2, v40
	v_exp_f32_e32 v22, v3
	v_sub_f32_e32 v3, v12, v197
	v_add_f32_e32 v2, v2, v4
	v_mul_f32_e32 v3, 0x3fb8aa3b, v3
	v_add_f32_e32 v2, v2, v6
	v_exp_f32_e32 v28, v3
	v_sub_f32_e32 v3, v192, v197
	v_add_f32_e32 v2, v2, v9
	v_mul_f32_e32 v3, 0x3fb8aa3b, v3
	v_add_f32_e32 v2, v2, v11
	v_exp_f32_e32 v32, v3
	v_add_f32_e32 v2, v2, v18
	v_add_f32_e32 v2, v2, v22
	v_add_f32_e32 v2, v2, v28
	v_add_f32_e32 v3, v2, v32
	v_sub_f32_e32 v2, v191, v197
	v_mul_f32_e32 v2, 0x3fb8aa3b, v2
	v_exp_f32_e32 v2, v2
	v_sub_f32_e32 v0, v0, v197
	v_mul_f32_e32 v0, 0x3fb8aa3b, v0
	v_exp_f32_e32 v0, v0
	v_add_f32_e32 v5, v3, v2
	v_sub_f32_e32 v3, v7, v197
	v_mul_f32_e32 v3, 0x3fb8aa3b, v3
	v_exp_f32_e32 v3, v3
	v_cvt_pk_bf16_f32 v70, v70, v71
	v_cvt_pk_bf16_f32 v71, v72, v73
	v_cvt_pk_bf16_f32 v72, v66, v67
	v_add_f32_e32 v7, v5, v3
	v_sub_f32_e32 v5, v193, v197
	v_mul_f32_e32 v5, 0x3fb8aa3b, v5
	v_exp_f32_e32 v5, v5
	v_add_u32_e32 v66, v115, v114
	v_add_u32_e32 v66, 0xd800, v66
	v_cvt_pk_bf16_f32 v73, v68, v69
	v_add_f32_e32 v12, v7, v5
	v_sub_f32_e32 v7, v195, v197
	v_mul_f32_e32 v7, 0x3fb8aa3b, v7
	v_exp_f32_e32 v7, v7
	ds_read2_b64 v[66:69], v66 offset1:4
	s_waitcnt lgkmcnt(0)
	v_mfma_f32_16x16x32_bf16 v[66:69], v[66:69], v[70:73], 0
	v_add_f32_e32 v15, v12, v7
	v_sub_f32_e32 v12, v194, v197
	v_mul_f32_e32 v12, 0x3fb8aa3b, v12
	v_exp_f32_e32 v12, v12
	s_nop 0
	v_add_f32_e32 v20, v15, v12
	v_sub_f32_e32 v15, v196, v197
	v_mul_f32_e32 v15, 0x3fb8aa3b, v15
	v_exp_f32_e32 v15, v15
	s_nop 0
	v_add_f32_e32 v24, v20, v15
	v_sub_f32_e32 v20, v198, v197
	v_mul_f32_e32 v20, 0x3fb8aa3b, v20
	v_exp_f32_e32 v20, v20
	s_nop 0
	v_add_f32_e32 v151, v24, v20
	v_sub_f32_e32 v24, v199, v197
	v_mul_f32_e32 v24, 0x3fb8aa3b, v24
	v_exp_f32_e32 v24, v24
	s_nop 0
	v_add_f32_e32 v151, v151, v24
	ds_bpermute_b32 v101, v101, v151
	s_waitcnt lgkmcnt(0)
	v_add_f32_e32 v101, v151, v101
	ds_bpermute_b32 v151, v155, v101
	s_waitcnt lgkmcnt(0)
	v_add_f32_e32 v101, v101, v151
	v_add_f32_e32 v0, v0, v101
	v_add_u32_e32 v101, v115, v116
	v_add_u32_e32 v101, 0xd800, v101
	ds_read2_b64 v[156:159], v101 offset1:4
	v_add_u32_e32 v101, v115, v117
	v_add_u32_e32 v101, 0xd800, v101
	ds_read2_b64 v[180:183], v101 offset1:4
	v_add_u32_e32 v101, v115, v118
	v_add_u32_e32 v101, 0xd800, v101
	ds_read2_b64 v[184:187], v101 offset1:4
	s_waitcnt lgkmcnt(2)
	v_mfma_f32_16x16x32_bf16 v[156:159], v[156:159], v[70:73], 0
	s_waitcnt lgkmcnt(1)
	v_mfma_f32_16x16x32_bf16 v[180:183], v[180:183], v[70:73], 0
	s_waitcnt lgkmcnt(0)
	v_mfma_f32_16x16x32_bf16 v[70:73], v[184:187], v[70:73], 0
	v_cvt_pk_bf16_f32 v62, v62, v63
	v_cvt_pk_bf16_f32 v63, v64, v65
	v_cvt_pk_bf16_f32 v64, v58, v59
	v_add_u32_e32 v58, v119, v114
	v_add_u32_e32 v58, 0xd800, v58
	v_cvt_pk_bf16_f32 v65, v60, v61
	ds_read2_b64 v[58:61], v58 offset1:4
	v_add_u32_e32 v101, v119, v117
	v_add_u32_e32 v101, 0xd800, v101
	s_waitcnt lgkmcnt(0)
; __global__ void __launch_bounds__(NTHREADS, 2) fwd_megakernel(Params p_arg) {
;     ...
;           for (int pp = 0; pp < 9; ++pp) {
;             union { bf16x8 v; uint32_t u[4]; } pf;
;             pf.u[0] = pack2(S[2*pp][0], S[2*pp][1]); pf.u[1] = pack2(S[2*pp][2], S[2*pp][3]);
;             pf.u[2] = pack2(S[2*pp+1][0], S[2*pp+1][1]); pf.u[3] = pack2(S[2*pp+1][2], S[2*pp+1][3]);
; #pragma unroll
;             for (int dt = 0; dt < 4; ++dt) {
;               union { bf16x8 v; uint2 h2[2]; } vfr;
;               const u16* vb = VT + (dt * 16 + fr) * 392 + (kt0 + 2 * pp) * 16 + fq * 4;
;               vfr.h2[0] = *(const uint2*)(vb);
;               vfr.h2[1] = *(const uint2*)(vb + 16);
;               O[dt] = __builtin_amdgcn_mfma_f32_16x16x32_bf16(vfr.v, pf.v, O[dt], 0, 0, 0);
;             }
;             __builtin_amdgcn_sched_barrier(0);
;           }
	v_mfma_f32_16x16x32_bf16 v[58:61], v[58:61], v[62:65], v[66:69]
	s_nop 2
	v_add_u32_e32 v66, v119, v116
	v_add_u32_e32 v66, 0xd800, v66
	ds_read2_b64 v[66:69], v66 offset1:4
	s_waitcnt lgkmcnt(0)
	v_mfma_f32_16x16x32_bf16 v[66:69], v[66:69], v[62:65], v[156:159]
	s_nop 2
	ds_read2_b64 v[156:159], v101 offset1:4
	v_add_u32_e32 v101, v119, v118
	v_add_u32_e32 v101, 0xd800, v101
	s_waitcnt lgkmcnt(0)
	v_mfma_f32_16x16x32_bf16 v[156:159], v[156:159], v[62:65], v[180:183]
	s_nop 2
	ds_read2_b64 v[180:183], v101 offset1:4
	s_waitcnt lgkmcnt(0)
	v_mfma_f32_16x16x32_bf16 v[62:65], v[180:183], v[62:65], v[70:73]
	s_nop 2
	v_cvt_pk_bf16_f32 v70, v35, v39
	v_add_u32_e32 v35, v120, v114
	v_add_u32_e32 v35, 0xd800, v35
	v_cvt_pk_bf16_f32 v71, v54, v55
	v_cvt_pk_bf16_f32 v72, v50, v56
	v_cvt_pk_bf16_f32 v73, v57, v53
	ds_read2_b64 v[54:57], v35 offset1:4
	v_add_u32_e32 v35, v120, v116
	v_add_u32_e32 v35, 0xd800, v35
	s_waitcnt lgkmcnt(0)
	v_mfma_f32_16x16x32_bf16 v[54:57], v[54:57], v[70:73], v[58:61]
	s_nop 2
	ds_read2_b64 v[58:61], v35 offset1:4
	v_add_u32_e32 v35, v120, v117
	v_add_u32_e32 v35, 0xd800, v35
	s_waitcnt lgkmcnt(0)
	v_mfma_f32_16x16x32_bf16 v[58:61], v[58:61], v[70:73], v[66:69]
	s_nop 2
	ds_read2_b64 v[66:69], v35 offset1:4
	v_add_u32_e32 v35, v120, v118
	v_add_u32_e32 v35, 0xd800, v35
	s_waitcnt lgkmcnt(0)
	v_mfma_f32_16x16x32_bf16 v[66:69], v[66:69], v[70:73], v[156:159]
	s_nop 2
	ds_read2_b64 v[156:159], v35 offset1:4
	s_waitcnt lgkmcnt(0)
	v_mfma_f32_16x16x32_bf16 v[62:65], v[156:159], v[70:73], v[62:65]
	v_cvt_pk_bf16_f32 v70, v27, v31
	v_add_u32_e32 v27, v121, v114
	v_add_u32_e32 v27, 0xd800, v27
	v_cvt_pk_bf16_f32 v73, v51, v52
	ds_read2_b64 v[50:53], v27 offset1:4
	v_add_u32_e32 v27, v121, v116
	v_cvt_pk_bf16_f32 v71, v37, v41
	v_cvt_pk_bf16_f32 v72, v46, v48
	v_add_u32_e32 v27, 0xd800, v27
	s_waitcnt lgkmcnt(0)
	v_mfma_f32_16x16x32_bf16 v[50:53], v[50:53], v[70:73], v[54:57]
	s_nop 2
	ds_read2_b64 v[54:57], v27 offset1:4
	v_add_u32_e32 v27, v121, v117
	v_add_u32_e32 v27, 0xd800, v27
	s_waitcnt lgkmcnt(0)
	v_mfma_f32_16x16x32_bf16 v[54:57], v[54:57], v[70:73], v[58:61]
	s_nop 2
	ds_read2_b64 v[58:61], v27 offset1:4
	v_add_u32_e32 v27, v121, v118
	v_add_u32_e32 v27, 0xd800, v27
	s_waitcnt lgkmcnt(0)
	v_mfma_f32_16x16x32_bf16 v[58:61], v[58:61], v[70:73], v[66:69]
	s_nop 2
	ds_read2_b64 v[66:69], v27 offset1:4
	s_waitcnt lgkmcnt(0)
	v_mfma_f32_16x16x32_bf16 v[62:65], v[66:69], v[70:73], v[62:65]
	v_cvt_pk_bf16_f32 v66, v19, v23
	v_add_u32_e32 v19, v122, v114
	v_add_u32_e32 v19, 0xd800, v19
	v_cvt_pk_bf16_f32 v69, v47, v49
	ds_read2_b64 v[46:49], v19 offset1:4
	v_add_u32_e32 v19, v122, v116
	v_cvt_pk_bf16_f32 v67, v29, v33
	v_cvt_pk_bf16_f32 v68, v42, v44
	v_add_u32_e32 v19, 0xd800, v19
	s_waitcnt lgkmcnt(0)
	v_mfma_f32_16x16x32_bf16 v[46:49], v[46:49], v[66:69], v[50:53]
	s_nop 2
	ds_read2_b64 v[50:53], v19 offset1:4
	v_add_u32_e32 v19, v122, v117
	v_add_u32_e32 v19, 0xd800, v19
	s_waitcnt lgkmcnt(0)
	v_mfma_f32_16x16x32_bf16 v[50:53], v[50:53], v[66:69], v[54:57]
	s_nop 2
	ds_read2_b64 v[54:57], v19 offset1:4
	v_add_u32_e32 v19, v122, v118
	v_add_u32_e32 v19, 0xd800, v19
	s_waitcnt lgkmcnt(0)
	v_mfma_f32_16x16x32_bf16 v[54:57], v[54:57], v[66:69], v[58:61]
	s_nop 2
	ds_read2_b64 v[58:61], v19 offset1:4
	s_waitcnt lgkmcnt(0)
	v_mfma_f32_16x16x32_bf16 v[58:61], v[58:61], v[66:69], v[62:65]
	s_nop 2
	v_cvt_pk_bf16_f32 v62, v13, v16
	v_add_u32_e32 v13, v123, v114
	v_add_u32_e32 v13, 0xd800, v13
	v_cvt_pk_bf16_f32 v65, v43, v45
	ds_read2_b64 v[42:45], v13 offset1:4
	v_add_u32_e32 v13, v123, v116
	v_cvt_pk_bf16_f32 v63, v21, v25
	v_cvt_pk_bf16_f32 v64, v34, v38
	v_add_u32_e32 v13, 0xd800, v13
	s_waitcnt lgkmcnt(0)
	v_mfma_f32_16x16x32_bf16 v[42:45], v[42:45], v[62:65], v[46:49]
	s_nop 2
	ds_read2_b64 v[46:49], v13 offset1:4
	v_add_u32_e32 v13, v123, v117
	v_add_u32_e32 v13, 0xd800, v13
	s_waitcnt lgkmcnt(0)
	v_mfma_f32_16x16x32_bf16 v[46:49], v[46:49], v[62:65], v[50:53]
	s_nop 2
	ds_read2_b64 v[50:53], v13 offset1:4
	v_add_u32_e32 v13, v123, v118
	v_add_u32_e32 v13, 0xd800, v13
	s_waitcnt lgkmcnt(0)
	v_mfma_f32_16x16x32_bf16 v[50:53], v[50:53], v[62:65], v[54:57]
	s_nop 2
	ds_read2_b64 v[54:57], v13 offset1:4
	s_waitcnt lgkmcnt(0)
; __device__ __forceinline__ uint2 pack4(float a, float b, float c, float d) { return make_uint2(pack2(a, b), pack2(c, d)); }
; __device__ __forceinline__ float rcpf(float x) { return __builtin_amdgcn_rcpf(x); }
; __global__ void __launch_bounds__(NTHREADS, 2) fwd_megakernel(Params p_arg) {
;     ...
;           const float inv = rcpf(sum + __expf(sinkv - mx));
;           f32x4 O[4];
; #pragma unroll
;           for (int dt = 0; dt < 4; ++dt) O[dt] = f32x4{0.f, 0.f, 0.f, 0.f};
; #pragma unroll
;           for (int pp = 0; pp < 9; ++pp) {
;             union { bf16x8 v; uint32_t u[4]; } pf;
;             pf.u[0] = pack2(S[2*pp][0], S[2*pp][1]); pf.u[1] = pack2(S[2*pp][2], S[2*pp][3]);
;             pf.u[2] = pack2(S[2*pp+1][0], S[2*pp+1][1]); pf.u[3] = pack2(S[2*pp+1][2], S[2*pp+1][3]);
; #pragma unroll
;             for (int dt = 0; dt < 4; ++dt) {
;               union { bf16x8 v; uint2 h2[2]; } vfr;
;               const u16* vb = VT + (dt * 16 + fr) * 392 + (kt0 + 2 * pp) * 16 + fq * 4;
;               vfr.h2[0] = *(const uint2*)(vb);
;               vfr.h2[1] = *(const uint2*)(vb + 16);
;               O[dt] = __builtin_amdgcn_mfma_f32_16x16x32_bf16(vfr.v, pf.v, O[dt], 0, 0, 0);
;             }
;             __builtin_amdgcn_sched_barrier(0);
;           }
; #pragma unroll
;           for (int dp = 0; dp < 2; ++dp)
;             store_pair16(ABp + tokq * 1024 + 512 + h * 64 + dp * 32, fq,
;                          pack4(O[2*dp][0] * inv, O[2*dp][1] * inv, O[2*dp][2] * inv, O[2*dp][3] * inv),
;                          pack4(O[2*dp+1][0] * inv, O[2*dp+1][1] * inv, O[2*dp+1][2] * inv, O[2*dp+1][3] * inv));
;         }
	v_mfma_f32_16x16x32_bf16 v[54:57], v[54:57], v[62:65], v[58:61]
	s_nop 2
	v_cvt_pk_bf16_f32 v58, v8, v10
	v_add_u32_e32 v8, v124, v114
	v_add_u32_e32 v8, 0xd800, v8
	v_cvt_pk_bf16_f32 v61, v36, v40
	ds_read2_b64 v[34:37], v8 offset1:4
	v_add_u32_e32 v8, v124, v116
	v_add_u32_e32 v8, 0xd800, v8
	ds_read2_b64 v[38:41], v8 offset1:4
	v_add_u32_e32 v8, v124, v117
	v_cvt_pk_bf16_f32 v59, v14, v17
	v_cvt_pk_bf16_f32 v60, v26, v30
	v_add_u32_e32 v8, 0xd800, v8
	s_waitcnt lgkmcnt(1)
	v_mfma_f32_16x16x32_bf16 v[34:37], v[34:37], v[58:61], v[42:45]
	s_nop 2
	ds_read2_b64 v[42:45], v8 offset1:4
	v_add_u32_e32 v8, v124, v118
	v_add_u32_e32 v8, 0xd800, v8
	s_waitcnt lgkmcnt(1)
	v_mfma_f32_16x16x32_bf16 v[38:41], v[38:41], v[58:61], v[46:49]
	s_nop 2
	ds_read2_b64 v[46:49], v8 offset1:4
	s_waitcnt lgkmcnt(1)
	v_mfma_f32_16x16x32_bf16 v[42:45], v[42:45], v[58:61], v[50:53]
	s_waitcnt lgkmcnt(0)
	v_mfma_f32_16x16x32_bf16 v[46:49], v[46:49], v[58:61], v[54:57]
	v_cvt_pk_bf16_f32 v8, v4, v6
	v_add_u32_e32 v4, v125, v114
	v_add_u32_e32 v4, 0xd800, v4
	v_cvt_pk_bf16_f32 v10, v18, v22
	ds_read2_b64 v[16:19], v4 offset1:4
	v_add_u32_e32 v4, v125, v116
	v_add_u32_e32 v4, 0xd800, v4
	v_cvt_pk_bf16_f32 v9, v9, v11
	v_cvt_pk_bf16_f32 v11, v28, v32
	ds_read2_b64 v[26:29], v4 offset1:4
	v_add_u32_e32 v4, v125, v117
	v_add_u32_e32 v4, 0xd800, v4
	ds_read2_b64 v[30:33], v4 offset1:4
	v_add_u32_e32 v4, v125, v118
	v_add_u32_e32 v4, 0xd800, v4
	s_waitcnt lgkmcnt(2)
	v_mfma_f32_16x16x32_bf16 v[16:19], v[16:19], v[8:11], v[34:37]
	s_nop 2
	ds_read2_b64 v[34:37], v4 offset1:4
	s_waitcnt lgkmcnt(2)
	v_mfma_f32_16x16x32_bf16 v[26:29], v[26:29], v[8:11], v[38:41]
	s_waitcnt lgkmcnt(1)
	v_mfma_f32_16x16x32_bf16 v[30:33], v[30:33], v[8:11], v[42:45]
	s_waitcnt lgkmcnt(0)
	v_mfma_f32_16x16x32_bf16 v[8:11], v[34:37], v[8:11], v[46:49]
	v_add_u32_e32 v6, v126, v114
	v_add_u32_e32 v6, 0xd800, v6
	v_cvt_pk_bf16_f32 v4, v12, v15
	ds_read2_b64 v[12:15], v6 offset1:4
	v_add_u32_e32 v6, v126, v116
	v_cvt_pk_bf16_f32 v2, v2, v3
	v_cvt_pk_bf16_f32 v3, v5, v7
	v_cvt_pk_bf16_f32 v5, v20, v24
	v_add_u32_e32 v6, 0xd800, v6
	s_waitcnt lgkmcnt(0)
	v_mfma_f32_16x16x32_bf16 v[12:15], v[12:15], v[2:5], v[16:19]
	s_nop 2
	ds_read2_b64 v[16:19], v6 offset1:4
	v_add_u32_e32 v6, v126, v117
	v_add_u32_e32 v6, 0xd800, v6
	ds_read2_b64 v[20:23], v6 offset1:4
	v_add_u32_e32 v6, v126, v118
	v_add_u32_e32 v6, 0xd800, v6
	s_waitcnt lgkmcnt(1)
	v_mfma_f32_16x16x32_bf16 v[16:19], v[16:19], v[2:5], v[26:29]
	s_nop 2
	ds_read2_b64 v[24:27], v6 offset1:4
	s_waitcnt lgkmcnt(1)
	v_mfma_f32_16x16x32_bf16 v[20:23], v[20:23], v[2:5], v[30:33]
	s_waitcnt lgkmcnt(0)
	v_mfma_f32_16x16x32_bf16 v[2:5], v[24:27], v[2:5], v[8:11]
	v_rcp_f32_e32 v0, v0
	s_nop 1
	v_lshl_add_u64 v[10:11], v[110:111], 0, s[24:25]
	s_add_u32 s24, s24, 0x80
	s_addc_u32 s25, s25, 0
	s_add_i32 s0, s0, 1
	s_add_u32 s12, s12, 4
	v_pk_mul_f32 v[6:7], v[0:1], v[12:13] op_sel_hi:[0,1]
	v_pk_mul_f32 v[8:9], v[0:1], v[14:15] op_sel_hi:[0,1]
	v_pk_mul_f32 v[12:13], v[0:1], v[16:17] op_sel_hi:[0,1]
	v_pk_mul_f32 v[14:15], v[0:1], v[18:19] op_sel_hi:[0,1]
	s_addc_u32 s13, s13, 0
	v_pk_mul_f32 v[16:17], v[0:1], v[20:21] op_sel_hi:[0,1]
	v_pk_mul_f32 v[18:19], v[0:1], v[22:23] op_sel_hi:[0,1]
	v_pk_mul_f32 v[20:21], v[0:1], v[2:3] op_sel_hi:[0,1]
	v_pk_mul_f32 v[22:23], v[0:1], v[4:5] op_sel_hi:[0,1]
	v_cvt_pk_bf16_f32 v2, v6, v7
	v_cvt_pk_bf16_f32 v3, v8, v9
	v_cvt_pk_bf16_f32 v4, v12, v13
	v_cvt_pk_bf16_f32 v5, v14, v15
	s_cmpk_eq_i32 s24, 0x200
	v_cvt_pk_bf16_f32 v6, v16, v17
	v_cvt_pk_bf16_f32 v7, v18, v19
	v_cvt_pk_bf16_f32 v8, v20, v21
	v_cvt_pk_bf16_f32 v9, v22, v23
	v_permlane16_swap_b32_e32 v2, v4
	v_permlane16_swap_b32_e32 v3, v5
	v_permlane16_swap_b32_e32 v6, v8
	v_permlane16_swap_b32_e32 v7, v9
	global_store_dwordx4 v[10:11], v[2:5], off offset:-64
	global_store_dwordx4 v[10:11], v[6:9], off
	s_cbranch_scc0 .LBB0_312
	s_mov_b32 s28, 1
	s_mov_b64 s[12:13], 0
	s_and_b64 vcc, exec, s[92:93]
	s_barrier
	s_cbranch_vccz .LBB0_299
	s_add_i32 s99, s99, s3
	s_add_i32 s98, s98, s3
	s_cmpk_gt_i32 s99, 0xff
	s_cbranch_scc0 .LBB0_294
